# loop-bottom counter/pointer SALU interleaved into the last MFMA block (out of the next load phase)
# baseline (speedup 1.0000x reference)
.LBB0_132:
	ds_read_b128 v[128:131], v179
	ds_read_b128 v[132:135], v179 offset:1024
	ds_read_b128 v[136:139], v179 offset:2048
	ds_read_b128 v[140:143], v179 offset:3072
	ds_read_b128 v[166:169], v180
	ds_read_b128 v[170:173], v180 offset:1024
	ds_read_b128 v[184:187], v180 offset:2048
	ds_read_b128 v[188:191], v180 offset:3072
	s_add_u32 s16, s74, 0xfff00080
	s_addc_u32 s17, s75, -1
	s_cmp_eq_u32 vcc_hi, 60
	s_cselect_b32 s79, s57, s17
	s_cselect_b32 s78, s95, s16
	s_cselect_b32 s77, s55, vcc_lo
	s_cselect_b32 s76, s96, s97
	v_lshl_add_u64 v[174:175], s[74:75], 0, v[158:159]
	s_add_i32 m0, s81, 0xc000
	ds_read_b128 v[192:195], v181
	ds_read_b128 v[196:199], v181 offset:1024
	ds_read_b128 v[200:203], v181 offset:2048
	ds_read_b128 v[206:209], v181 offset:3072
	ds_read_b128 v[210:213], v181 offset:4096
	ds_read_b128 v[214:217], v181 offset:5120
	ds_read_b128 v[218:221], v181 offset:6144
	ds_read_b128 v[222:225], v181 offset:7168
	global_load_lds_dwordx4 v[174:175], off
	v_lshl_add_u64 v[174:175], s[74:75], 0, v[160:161]
	s_add_i32 m0, s81, 0xe000
	s_nop 0
	global_load_lds_dwordx4 v[174:175], off
	s_waitcnt vmcnt(8)
	s_waitcnt lgkmcnt(0)
	s_setprio 1
	s_barrier
	v_mfma_f32_16x16x32_bf16 v[124:127], v[128:131], v[192:195], v[124:127]
	v_mfma_f32_16x16x32_bf16 v[120:123], v[136:139], v[192:195], v[120:123]
	v_mfma_f32_16x16x32_bf16 v[108:111], v[128:131], v[200:203], v[108:111]
	v_mfma_f32_16x16x32_bf16 v[104:107], v[136:139], v[200:203], v[104:107]
	v_mfma_f32_16x16x32_bf16 v[92:95], v[128:131], v[210:213], v[92:95]
	v_mfma_f32_16x16x32_bf16 v[88:91], v[136:139], v[210:213], v[88:91]
	v_mfma_f32_16x16x32_bf16 v[76:79], v[128:131], v[218:221], v[76:79]
	v_mfma_f32_16x16x32_bf16 v[72:75], v[136:139], v[218:221], v[72:75]
	v_mfma_f32_16x16x32_bf16 v[124:127], v[132:135], v[196:199], v[124:127]
	v_mfma_f32_16x16x32_bf16 v[120:123], v[140:143], v[196:199], v[120:123]
	v_mfma_f32_16x16x32_bf16 v[108:111], v[132:135], v[206:209], v[108:111]
	v_mfma_f32_16x16x32_bf16 v[104:107], v[140:143], v[206:209], v[104:107]
	v_mfma_f32_16x16x32_bf16 v[92:95], v[132:135], v[214:217], v[92:95]
	v_mfma_f32_16x16x32_bf16 v[88:91], v[140:143], v[214:217], v[88:91]
	v_mfma_f32_16x16x32_bf16 v[76:79], v[132:135], v[222:225], v[76:79]
	v_mfma_f32_16x16x32_bf16 v[72:75], v[140:143], v[222:225], v[72:75]
	v_mfma_f32_16x16x32_bf16 v[116:119], v[166:169], v[192:195], v[116:119]
	v_mfma_f32_16x16x32_bf16 v[112:115], v[184:187], v[192:195], v[112:115]
	v_mfma_f32_16x16x32_bf16 v[100:103], v[166:169], v[200:203], v[100:103]
	v_mfma_f32_16x16x32_bf16 v[96:99], v[184:187], v[200:203], v[96:99]
	v_mfma_f32_16x16x32_bf16 v[84:87], v[166:169], v[210:213], v[84:87]
	v_mfma_f32_16x16x32_bf16 v[80:83], v[184:187], v[210:213], v[80:83]
	v_mfma_f32_16x16x32_bf16 v[68:71], v[166:169], v[218:221], v[68:71]
	v_mfma_f32_16x16x32_bf16 v[64:67], v[184:187], v[218:221], v[64:67]
	v_mfma_f32_16x16x32_bf16 v[116:119], v[170:173], v[196:199], v[116:119]
	v_mfma_f32_16x16x32_bf16 v[112:115], v[188:191], v[196:199], v[112:115]
	v_mfma_f32_16x16x32_bf16 v[100:103], v[170:173], v[206:209], v[100:103]
	v_mfma_f32_16x16x32_bf16 v[96:99], v[188:191], v[206:209], v[96:99]
	v_mfma_f32_16x16x32_bf16 v[84:87], v[170:173], v[214:217], v[84:87]
	v_mfma_f32_16x16x32_bf16 v[80:83], v[188:191], v[214:217], v[80:83]
	v_mfma_f32_16x16x32_bf16 v[68:71], v[170:173], v[222:225], v[68:71]
	v_mfma_f32_16x16x32_bf16 v[64:67], v[188:191], v[222:225], v[64:67]
	s_barrier
	s_setprio 0
	s_add_i32 s16, s93, s80
	v_lshl_add_u64 v[174:175], s[76:77], 0, v[146:147]
	s_mov_b32 m0, s16
	ds_read_b128 v[192:195], v181 offset:16384
	ds_read_b128 v[196:199], v181 offset:17408
	ds_read_b128 v[200:203], v181 offset:18432
	ds_read_b128 v[206:209], v181 offset:19456
	ds_read_b128 v[210:213], v181 offset:20480
	ds_read_b128 v[214:217], v181 offset:21504
	ds_read_b128 v[218:221], v181 offset:22528
	ds_read_b128 v[222:225], v181 offset:23552
	global_load_lds_dwordx4 v[174:175], off
	s_add_i32 m0, s16, 0x2000
	s_add_u32 s16, s76, 0x100000
	v_lshl_add_u64 v[228:229], s[76:77], 0, v[150:151]
	s_addc_u32 s17, s77, 0
	s_add_i32 s3, s94, s80
	global_load_lds_dwordx4 v[228:229], off
	v_lshl_add_u64 v[230:231], s[16:17], 0, v[146:147]
	s_mov_b32 m0, s3
	v_lshl_add_u64 v[232:233], s[78:79], 0, v[148:149]
	global_load_lds_dwordx4 v[230:231], off
	v_lshl_add_u64 v[230:231], s[16:17], 0, v[150:151]
	s_add_i32 m0, s3, 0x2000
	s_nop 0
	global_load_lds_dwordx4 v[230:231], off
	v_lshl_add_u64 v[230:231], s[78:79], 0, v[144:145]
	s_mov_b32 m0, s81
	s_nop 0
	global_load_lds_dwordx4 v[230:231], off
	s_mov_b32 m0, s82
	s_nop 0
	global_load_lds_dwordx4 v[232:233], off
	s_waitcnt vmcnt(8)
	s_waitcnt lgkmcnt(0)
	s_setprio 1
	s_barrier
	v_mfma_f32_16x16x32_bf16 v[60:63], v[128:131], v[192:195], v[60:63]
	v_mfma_f32_16x16x32_bf16 v[56:59], v[136:139], v[192:195], v[56:59]
	v_mfma_f32_16x16x32_bf16 v[44:47], v[128:131], v[200:203], v[44:47]
	v_mfma_f32_16x16x32_bf16 v[40:43], v[136:139], v[200:203], v[40:43]
	v_mfma_f32_16x16x32_bf16 v[28:31], v[128:131], v[210:213], v[28:31]
	v_mfma_f32_16x16x32_bf16 v[24:27], v[136:139], v[210:213], v[24:27]
	v_mfma_f32_16x16x32_bf16 v[12:15], v[128:131], v[218:221], v[12:15]
	v_mfma_f32_16x16x32_bf16 v[8:11], v[136:139], v[218:221], v[8:11]
	v_mfma_f32_16x16x32_bf16 v[60:63], v[132:135], v[196:199], v[60:63]
	v_mfma_f32_16x16x32_bf16 v[56:59], v[140:143], v[196:199], v[56:59]
	v_mfma_f32_16x16x32_bf16 v[44:47], v[132:135], v[206:209], v[44:47]
	v_mfma_f32_16x16x32_bf16 v[40:43], v[140:143], v[206:209], v[40:43]
	v_mfma_f32_16x16x32_bf16 v[28:31], v[132:135], v[214:217], v[28:31]
	v_mfma_f32_16x16x32_bf16 v[24:27], v[140:143], v[214:217], v[24:27]
	v_mfma_f32_16x16x32_bf16 v[12:15], v[132:135], v[222:225], v[12:15]
	v_mfma_f32_16x16x32_bf16 v[8:11], v[140:143], v[222:225], v[8:11]
	v_mfma_f32_16x16x32_bf16 v[52:55], v[166:169], v[192:195], v[52:55]
	v_mfma_f32_16x16x32_bf16 v[48:51], v[184:187], v[192:195], v[48:51]
	v_mfma_f32_16x16x32_bf16 v[36:39], v[166:169], v[200:203], v[36:39]
	v_mfma_f32_16x16x32_bf16 v[32:35], v[184:187], v[200:203], v[32:35]
	v_mfma_f32_16x16x32_bf16 v[20:23], v[166:169], v[210:213], v[20:23]
	v_mfma_f32_16x16x32_bf16 v[16:19], v[184:187], v[210:213], v[16:19]
	v_mfma_f32_16x16x32_bf16 v[4:7], v[166:169], v[218:221], v[4:7]
	v_mfma_f32_16x16x32_bf16 v[0:3], v[184:187], v[218:221], v[0:3]
	v_mfma_f32_16x16x32_bf16 v[52:55], v[170:173], v[196:199], v[52:55]
	v_mfma_f32_16x16x32_bf16 v[48:51], v[188:191], v[196:199], v[48:51]
	v_mfma_f32_16x16x32_bf16 v[36:39], v[170:173], v[206:209], v[36:39]
	v_mfma_f32_16x16x32_bf16 v[32:35], v[188:191], v[206:209], v[32:35]
	v_mfma_f32_16x16x32_bf16 v[20:23], v[170:173], v[214:217], v[20:23]
	v_mfma_f32_16x16x32_bf16 v[16:19], v[188:191], v[214:217], v[16:19]
	v_mfma_f32_16x16x32_bf16 v[4:7], v[170:173], v[222:225], v[4:7]
	v_mfma_f32_16x16x32_bf16 v[0:3], v[188:191], v[222:225], v[0:3]
	s_barrier
	s_setprio 0
	s_add_i32 s3, 0, 0x18000
	s_add_i32 s33, 0, 0x1c000
	v_add_u32_e32 v140, s3, v177
	v_add_u32_e32 v152, s33, v177
	ds_read_b128 v[128:131], v140
	ds_read_b128 v[132:135], v140 offset:1024
	ds_read_b128 v[136:139], v140 offset:2048
	ds_read_b128 v[140:143], v140 offset:3072
	ds_read_b128 v[166:169], v152
	ds_read_b128 v[170:173], v152 offset:1024
	ds_read_b128 v[184:187], v152 offset:2048
	ds_read_b128 v[188:191], v152 offset:3072
	s_add_u32 s16, s78, 0x100000
	s_addc_u32 s17, s79, 0
	s_mov_b32 m0, s83
	v_lshl_add_u64 v[234:235], s[16:17], 0, v[144:145]
	ds_read_b128 v[192:195], v181 offset:32768
	ds_read_b128 v[196:199], v181 offset:33792
	ds_read_b128 v[200:203], v181 offset:34816
	ds_read_b128 v[206:209], v181 offset:35840
	ds_read_b128 v[210:213], v181 offset:36864
	ds_read_b128 v[214:217], v181 offset:37888
	ds_read_b128 v[218:221], v181 offset:38912
	ds_read_b128 v[222:225], v181 offset:39936
	global_load_lds_dwordx4 v[234:235], off
	v_lshl_add_u64 v[234:235], s[16:17], 0, v[148:149]
	s_mov_b32 m0, s84
	s_nop 0
	global_load_lds_dwordx4 v[234:235], off
	s_waitcnt vmcnt(8)
	s_waitcnt lgkmcnt(0)
	s_setprio 1
	s_barrier
	v_mfma_f32_16x16x32_bf16 v[124:127], v[128:131], v[192:195], v[124:127]
	v_mfma_f32_16x16x32_bf16 v[120:123], v[136:139], v[192:195], v[120:123]
	v_mfma_f32_16x16x32_bf16 v[108:111], v[128:131], v[200:203], v[108:111]
	v_mfma_f32_16x16x32_bf16 v[104:107], v[136:139], v[200:203], v[104:107]
	v_mfma_f32_16x16x32_bf16 v[92:95], v[128:131], v[210:213], v[92:95]
	v_mfma_f32_16x16x32_bf16 v[88:91], v[136:139], v[210:213], v[88:91]
	v_mfma_f32_16x16x32_bf16 v[76:79], v[128:131], v[218:221], v[76:79]
	v_mfma_f32_16x16x32_bf16 v[72:75], v[136:139], v[218:221], v[72:75]
	v_mfma_f32_16x16x32_bf16 v[124:127], v[132:135], v[196:199], v[124:127]
	v_mfma_f32_16x16x32_bf16 v[120:123], v[140:143], v[196:199], v[120:123]
	v_mfma_f32_16x16x32_bf16 v[108:111], v[132:135], v[206:209], v[108:111]
	v_mfma_f32_16x16x32_bf16 v[104:107], v[140:143], v[206:209], v[104:107]
	v_mfma_f32_16x16x32_bf16 v[92:95], v[132:135], v[214:217], v[92:95]
	v_mfma_f32_16x16x32_bf16 v[88:91], v[140:143], v[214:217], v[88:91]
	v_mfma_f32_16x16x32_bf16 v[76:79], v[132:135], v[222:225], v[76:79]
	v_mfma_f32_16x16x32_bf16 v[72:75], v[140:143], v[222:225], v[72:75]
	v_mfma_f32_16x16x32_bf16 v[116:119], v[166:169], v[192:195], v[116:119]
	v_mfma_f32_16x16x32_bf16 v[112:115], v[184:187], v[192:195], v[112:115]
	v_mfma_f32_16x16x32_bf16 v[100:103], v[166:169], v[200:203], v[100:103]
	v_mfma_f32_16x16x32_bf16 v[96:99], v[184:187], v[200:203], v[96:99]
	v_mfma_f32_16x16x32_bf16 v[84:87], v[166:169], v[210:213], v[84:87]
	v_mfma_f32_16x16x32_bf16 v[80:83], v[184:187], v[210:213], v[80:83]
	v_mfma_f32_16x16x32_bf16 v[68:71], v[166:169], v[218:221], v[68:71]
	v_mfma_f32_16x16x32_bf16 v[64:67], v[184:187], v[218:221], v[64:67]
	v_mfma_f32_16x16x32_bf16 v[116:119], v[170:173], v[196:199], v[116:119]
	v_mfma_f32_16x16x32_bf16 v[112:115], v[188:191], v[196:199], v[112:115]
	v_mfma_f32_16x16x32_bf16 v[100:103], v[170:173], v[206:209], v[100:103]
	v_mfma_f32_16x16x32_bf16 v[96:99], v[188:191], v[206:209], v[96:99]
	v_mfma_f32_16x16x32_bf16 v[84:87], v[170:173], v[214:217], v[84:87]
	v_mfma_f32_16x16x32_bf16 v[80:83], v[188:191], v[214:217], v[80:83]
	v_mfma_f32_16x16x32_bf16 v[68:71], v[170:173], v[222:225], v[68:71]
	v_mfma_f32_16x16x32_bf16 v[64:67], v[188:191], v[222:225], v[64:67]
	s_barrier
	s_setprio 0
	s_add_i32 s3, s3, s80
	v_lshl_add_u64 v[174:175], v[174:175], 0, s[42:43]
	s_mov_b32 m0, s3
	ds_read_b128 v[192:195], v181 offset:49152
	ds_read_b128 v[196:199], v181 offset:50176
	ds_read_b128 v[200:203], v181 offset:51200
	ds_read_b128 v[206:209], v181 offset:52224
	ds_read_b128 v[210:213], v181 offset:53248
	ds_read_b128 v[214:217], v181 offset:54272
	ds_read_b128 v[218:221], v181 offset:55296
	ds_read_b128 v[222:225], v181 offset:56320
	global_load_lds_dwordx4 v[174:175], off
	s_add_i32 m0, s3, 0x2000
	s_add_u32 s16, s76, 0x100800
	v_lshl_add_u64 v[174:175], v[228:229], 0, s[42:43]
	s_addc_u32 s17, s77, 0
	s_add_i32 s3, s33, s80
	global_load_lds_dwordx4 v[174:175], off
	v_lshl_add_u64 v[174:175], s[16:17], 0, v[146:147]
	s_mov_b32 m0, s3
	s_nop 0
	global_load_lds_dwordx4 v[174:175], off
	v_lshl_add_u64 v[174:175], s[16:17], 0, v[150:151]
	s_add_i32 m0, s3, 0x2000
	s_nop 0
	global_load_lds_dwordx4 v[174:175], off
	v_lshl_add_u64 v[174:175], v[230:231], 0, s[44:45]
	s_mov_b32 m0, s86
	s_nop 0
	global_load_lds_dwordx4 v[174:175], off
	v_lshl_add_u64 v[174:175], v[232:233], 0, s[44:45]
	s_mov_b32 m0, s87
	s_nop 0
	global_load_lds_dwordx4 v[174:175], off
	s_waitcnt vmcnt(8)
	s_waitcnt lgkmcnt(0)
	s_setprio 1
	s_barrier
	v_mfma_f32_16x16x32_bf16 v[60:63], v[128:131], v[192:195], v[60:63]
	v_mfma_f32_16x16x32_bf16 v[56:59], v[136:139], v[192:195], v[56:59]
	v_mfma_f32_16x16x32_bf16 v[44:47], v[128:131], v[200:203], v[44:47]
	v_mfma_f32_16x16x32_bf16 v[40:43], v[136:139], v[200:203], v[40:43]
	v_mfma_f32_16x16x32_bf16 v[28:31], v[128:131], v[210:213], v[28:31]
	v_mfma_f32_16x16x32_bf16 v[24:27], v[136:139], v[210:213], v[24:27]
	v_mfma_f32_16x16x32_bf16 v[12:15], v[128:131], v[218:221], v[12:15]
	v_mfma_f32_16x16x32_bf16 v[8:11], v[136:139], v[218:221], v[8:11]
	v_mfma_f32_16x16x32_bf16 v[60:63], v[132:135], v[196:199], v[60:63]
	v_mfma_f32_16x16x32_bf16 v[56:59], v[140:143], v[196:199], v[56:59]
	v_mfma_f32_16x16x32_bf16 v[44:47], v[132:135], v[206:209], v[44:47]
	v_mfma_f32_16x16x32_bf16 v[40:43], v[140:143], v[206:209], v[40:43]
	v_mfma_f32_16x16x32_bf16 v[28:31], v[132:135], v[214:217], v[28:31]
	v_mfma_f32_16x16x32_bf16 v[24:27], v[140:143], v[214:217], v[24:27]
	v_mfma_f32_16x16x32_bf16 v[12:15], v[132:135], v[222:225], v[12:15]
	v_mfma_f32_16x16x32_bf16 v[8:11], v[140:143], v[222:225], v[8:11]
	v_mfma_f32_16x16x32_bf16 v[52:55], v[166:169], v[192:195], v[52:55]
	v_mfma_f32_16x16x32_bf16 v[48:51], v[184:187], v[192:195], v[48:51]
	v_mfma_f32_16x16x32_bf16 v[36:39], v[166:169], v[200:203], v[36:39]
	v_mfma_f32_16x16x32_bf16 v[32:35], v[184:187], v[200:203], v[32:35]
	v_mfma_f32_16x16x32_bf16 v[20:23], v[166:169], v[210:213], v[20:23]
	v_mfma_f32_16x16x32_bf16 v[16:19], v[184:187], v[210:213], v[16:19]
	v_mfma_f32_16x16x32_bf16 v[4:7], v[166:169], v[218:221], v[4:7]
	v_mfma_f32_16x16x32_bf16 v[0:3], v[184:187], v[218:221], v[0:3]
	v_mfma_f32_16x16x32_bf16 v[52:55], v[170:173], v[196:199], v[52:55]
	v_mfma_f32_16x16x32_bf16 v[48:51], v[188:191], v[196:199], v[48:51]
	v_mfma_f32_16x16x32_bf16 v[36:39], v[170:173], v[206:209], v[36:39]
	s_add_i32 vcc_hi, vcc_hi, 2
	v_mfma_f32_16x16x32_bf16 v[32:35], v[188:191], v[206:209], v[32:35]
	s_add_u32 s97, s97, 0x1000
	v_mfma_f32_16x16x32_bf16 v[20:23], v[170:173], v[214:217], v[20:23]
	s_addc_u32 vcc_lo, vcc_lo, 0
	v_mfma_f32_16x16x32_bf16 v[16:19], v[188:191], v[214:217], v[16:19]
	s_add_u32 s74, s74, 0x100
	v_mfma_f32_16x16x32_bf16 v[4:7], v[170:173], v[222:225], v[4:7]
	s_addc_u32 s75, s75, 0
	v_mfma_f32_16x16x32_bf16 v[0:3], v[188:191], v[222:225], v[0:3]
	s_cmp_gt_u32 vcc_hi, 61
	s_barrier
	s_setprio 0
	s_cbranch_scc0 .LBB0_132
	s_and_b64 vcc, exec, s[46:47]
	s_cbranch_vccz .LBB0_135
	s_barrier

.LBB0_432:
	ds_read_b128 v[128:131], v161
	ds_read_b128 v[132:135], v161 offset:1024
	ds_read_b128 v[136:139], v161 offset:2048
	ds_read_b128 v[140:143], v161 offset:3072
	ds_read_b128 v[164:167], v162
	ds_read_b128 v[168:171], v162 offset:1024
	ds_read_b128 v[172:175], v162 offset:2048
	ds_read_b128 v[176:179], v162 offset:3072
	s_add_u32 s3, s70, 0xfff80080
	s_addc_u32 s16, s71, -1
	s_cmp_eq_u32 vcc_hi, 4
	s_cselect_b32 s75, s93, s16
	s_cselect_b32 s74, s94, s3
	s_cselect_b32 s73, s95, vcc_lo
	s_cselect_b32 s72, s96, s97
	v_lshl_add_u64 v[156:157], s[70:71], 0, v[152:153]
	s_add_i32 m0, s1, 0xc000
	ds_read_b128 v[180:183], v163
	ds_read_b128 v[184:187], v163 offset:1024
	ds_read_b128 v[188:191], v163 offset:2048
	ds_read_b128 v[192:195], v163 offset:3072
	ds_read_b128 v[196:199], v163 offset:4096
	ds_read_b128 v[200:203], v163 offset:5120
	ds_read_b128 v[206:209], v163 offset:6144
	ds_read_b128 v[210:213], v163 offset:7168
	global_load_lds_dwordx4 v[156:157], off
	v_lshl_add_u64 v[156:157], s[70:71], 0, v[154:155]
	s_add_i32 m0, s1, 0xe000
	s_nop 0
	global_load_lds_dwordx4 v[156:157], off
	s_waitcnt vmcnt(8)
	s_waitcnt lgkmcnt(0)
	s_setprio 1
	s_barrier
	v_mfma_f32_16x16x32_bf16 v[124:127], v[128:131], v[180:183], v[124:127]
	v_mfma_f32_16x16x32_bf16 v[120:123], v[136:139], v[180:183], v[120:123]
	v_mfma_f32_16x16x32_bf16 v[116:119], v[128:131], v[188:191], v[116:119]
	v_mfma_f32_16x16x32_bf16 v[112:115], v[136:139], v[188:191], v[112:115]
	v_mfma_f32_16x16x32_bf16 v[108:111], v[128:131], v[196:199], v[108:111]
	v_mfma_f32_16x16x32_bf16 v[100:103], v[136:139], v[196:199], v[100:103]
	v_mfma_f32_16x16x32_bf16 v[76:79], v[128:131], v[206:209], v[76:79]
	v_mfma_f32_16x16x32_bf16 v[72:75], v[136:139], v[206:209], v[72:75]
	v_mfma_f32_16x16x32_bf16 v[124:127], v[132:135], v[184:187], v[124:127]
	v_mfma_f32_16x16x32_bf16 v[120:123], v[140:143], v[184:187], v[120:123]
	v_mfma_f32_16x16x32_bf16 v[116:119], v[132:135], v[192:195], v[116:119]
	v_mfma_f32_16x16x32_bf16 v[112:115], v[140:143], v[192:195], v[112:115]
	v_mfma_f32_16x16x32_bf16 v[108:111], v[132:135], v[200:203], v[108:111]
	v_mfma_f32_16x16x32_bf16 v[100:103], v[140:143], v[200:203], v[100:103]
	v_mfma_f32_16x16x32_bf16 v[76:79], v[132:135], v[210:213], v[76:79]
	v_mfma_f32_16x16x32_bf16 v[72:75], v[140:143], v[210:213], v[72:75]
	v_mfma_f32_16x16x32_bf16 v[104:107], v[164:167], v[180:183], v[104:107]
	v_mfma_f32_16x16x32_bf16 v[96:99], v[172:175], v[180:183], v[96:99]
	v_mfma_f32_16x16x32_bf16 v[92:95], v[164:167], v[188:191], v[92:95]
	v_mfma_f32_16x16x32_bf16 v[88:91], v[172:175], v[188:191], v[88:91]
	v_mfma_f32_16x16x32_bf16 v[84:87], v[164:167], v[196:199], v[84:87]
	v_mfma_f32_16x16x32_bf16 v[80:83], v[172:175], v[196:199], v[80:83]
	v_mfma_f32_16x16x32_bf16 v[68:71], v[164:167], v[206:209], v[68:71]
	v_mfma_f32_16x16x32_bf16 v[64:67], v[172:175], v[206:209], v[64:67]
	v_mfma_f32_16x16x32_bf16 v[104:107], v[168:171], v[184:187], v[104:107]
	v_mfma_f32_16x16x32_bf16 v[96:99], v[176:179], v[184:187], v[96:99]
	v_mfma_f32_16x16x32_bf16 v[92:95], v[168:171], v[192:195], v[92:95]
	v_mfma_f32_16x16x32_bf16 v[88:91], v[176:179], v[192:195], v[88:91]
	v_mfma_f32_16x16x32_bf16 v[84:87], v[168:171], v[200:203], v[84:87]
	v_mfma_f32_16x16x32_bf16 v[80:83], v[176:179], v[200:203], v[80:83]
	v_mfma_f32_16x16x32_bf16 v[68:71], v[168:171], v[210:213], v[68:71]
	v_mfma_f32_16x16x32_bf16 v[64:67], v[176:179], v[210:213], v[64:67]
	s_barrier
	s_setprio 0
	s_add_i32 s3, s85, s19
	v_lshl_add_u64 v[156:157], s[72:73], 0, v[148:149]
	s_mov_b32 m0, s3
	ds_read_b128 v[180:183], v163 offset:16384
	ds_read_b128 v[184:187], v163 offset:17408
	ds_read_b128 v[188:191], v163 offset:18432
	ds_read_b128 v[192:195], v163 offset:19456
	ds_read_b128 v[196:199], v163 offset:20480
	ds_read_b128 v[200:203], v163 offset:21504
	ds_read_b128 v[206:209], v163 offset:22528
	ds_read_b128 v[210:213], v163 offset:23552
	global_load_lds_dwordx4 v[156:157], off
	s_add_i32 m0, s3, 0x2000
	s_add_u32 s16, s72, 0x20000
	v_lshl_add_u64 v[214:215], s[72:73], 0, v[144:145]
	s_addc_u32 s17, s73, 0
	s_add_i32 s3, s86, s19
	global_load_lds_dwordx4 v[214:215], off
	v_lshl_add_u64 v[216:217], s[16:17], 0, v[148:149]
	s_mov_b32 m0, s3
	v_lshl_add_u64 v[218:219], s[74:75], 0, v[146:147]
	global_load_lds_dwordx4 v[216:217], off
	v_lshl_add_u64 v[216:217], s[16:17], 0, v[144:145]
	s_add_i32 m0, s3, 0x2000
	s_nop 0
	global_load_lds_dwordx4 v[216:217], off
	v_lshl_add_u64 v[216:217], s[74:75], 0, v[150:151]
	s_mov_b32 m0, s1
	s_nop 0
	global_load_lds_dwordx4 v[216:217], off
	s_mov_b32 m0, s79
	s_nop 0
	global_load_lds_dwordx4 v[218:219], off
	s_waitcnt vmcnt(8)
	s_waitcnt lgkmcnt(0)
	s_setprio 1
	s_barrier
	v_mfma_f32_16x16x32_bf16 v[60:63], v[128:131], v[180:183], v[60:63]
	v_mfma_f32_16x16x32_bf16 v[56:59], v[136:139], v[180:183], v[56:59]
	v_mfma_f32_16x16x32_bf16 v[48:51], v[128:131], v[188:191], v[48:51]
	v_mfma_f32_16x16x32_bf16 v[40:43], v[136:139], v[188:191], v[40:43]
	v_mfma_f32_16x16x32_bf16 v[32:35], v[128:131], v[196:199], v[32:35]
	v_mfma_f32_16x16x32_bf16 v[24:27], v[136:139], v[196:199], v[24:27]
	v_mfma_f32_16x16x32_bf16 v[16:19], v[128:131], v[206:209], v[16:19]
	v_mfma_f32_16x16x32_bf16 v[8:11], v[136:139], v[206:209], v[8:11]
	v_mfma_f32_16x16x32_bf16 v[60:63], v[132:135], v[184:187], v[60:63]
	v_mfma_f32_16x16x32_bf16 v[56:59], v[140:143], v[184:187], v[56:59]
	v_mfma_f32_16x16x32_bf16 v[48:51], v[132:135], v[192:195], v[48:51]
	v_mfma_f32_16x16x32_bf16 v[40:43], v[140:143], v[192:195], v[40:43]
	v_mfma_f32_16x16x32_bf16 v[32:35], v[132:135], v[200:203], v[32:35]
	v_mfma_f32_16x16x32_bf16 v[24:27], v[140:143], v[200:203], v[24:27]
	v_mfma_f32_16x16x32_bf16 v[16:19], v[132:135], v[210:213], v[16:19]
	v_mfma_f32_16x16x32_bf16 v[8:11], v[140:143], v[210:213], v[8:11]
	v_mfma_f32_16x16x32_bf16 v[52:55], v[164:167], v[180:183], v[52:55]
	v_mfma_f32_16x16x32_bf16 v[44:47], v[172:175], v[180:183], v[44:47]
	v_mfma_f32_16x16x32_bf16 v[36:39], v[164:167], v[188:191], v[36:39]
	v_mfma_f32_16x16x32_bf16 v[28:31], v[172:175], v[188:191], v[28:31]
	v_mfma_f32_16x16x32_bf16 v[20:23], v[164:167], v[196:199], v[20:23]
	v_mfma_f32_16x16x32_bf16 v[12:15], v[172:175], v[196:199], v[12:15]
	v_mfma_f32_16x16x32_bf16 v[4:7], v[164:167], v[206:209], v[4:7]
	v_mfma_f32_16x16x32_bf16 v[0:3], v[172:175], v[206:209], v[0:3]
	v_mfma_f32_16x16x32_bf16 v[52:55], v[168:171], v[184:187], v[52:55]
	v_mfma_f32_16x16x32_bf16 v[44:47], v[176:179], v[184:187], v[44:47]
	v_mfma_f32_16x16x32_bf16 v[36:39], v[168:171], v[192:195], v[36:39]
	v_mfma_f32_16x16x32_bf16 v[28:31], v[176:179], v[192:195], v[28:31]
	v_mfma_f32_16x16x32_bf16 v[20:23], v[168:171], v[200:203], v[20:23]
	v_mfma_f32_16x16x32_bf16 v[12:15], v[176:179], v[200:203], v[12:15]
	v_mfma_f32_16x16x32_bf16 v[4:7], v[168:171], v[210:213], v[4:7]
	v_mfma_f32_16x16x32_bf16 v[0:3], v[176:179], v[210:213], v[0:3]
	s_barrier
	s_setprio 0
	s_add_i32 s3, 0, 0x18000
	s_add_i32 s33, 0, 0x1c000
	v_add_u32_e32 v140, s3, v159
	v_add_u32_e32 v176, s33, v159
	ds_read_b128 v[128:131], v140
	ds_read_b128 v[132:135], v140 offset:1024
	ds_read_b128 v[136:139], v140 offset:2048
	ds_read_b128 v[140:143], v140 offset:3072
	ds_read_b128 v[164:167], v176
	ds_read_b128 v[168:171], v176 offset:1024
	ds_read_b128 v[172:175], v176 offset:2048
	ds_read_b128 v[176:179], v176 offset:3072
	s_add_u32 s16, s74, 0x80000
	s_addc_u32 s17, s75, 0
	s_mov_b32 m0, s80
	v_lshl_add_u64 v[220:221], s[16:17], 0, v[150:151]
	ds_read_b128 v[180:183], v163 offset:32768
	ds_read_b128 v[184:187], v163 offset:33792
	ds_read_b128 v[188:191], v163 offset:34816
	ds_read_b128 v[192:195], v163 offset:35840
	ds_read_b128 v[196:199], v163 offset:36864
	ds_read_b128 v[200:203], v163 offset:37888
	ds_read_b128 v[206:209], v163 offset:38912
	ds_read_b128 v[210:213], v163 offset:39936
	global_load_lds_dwordx4 v[220:221], off
	v_lshl_add_u64 v[220:221], s[16:17], 0, v[146:147]
	s_mov_b32 m0, s81
	s_nop 0
	global_load_lds_dwordx4 v[220:221], off
	s_waitcnt vmcnt(8)
	s_waitcnt lgkmcnt(0)
	s_setprio 1
	s_barrier
	v_mfma_f32_16x16x32_bf16 v[124:127], v[128:131], v[180:183], v[124:127]
	v_mfma_f32_16x16x32_bf16 v[120:123], v[136:139], v[180:183], v[120:123]
	v_mfma_f32_16x16x32_bf16 v[116:119], v[128:131], v[188:191], v[116:119]
	v_mfma_f32_16x16x32_bf16 v[112:115], v[136:139], v[188:191], v[112:115]
	v_mfma_f32_16x16x32_bf16 v[108:111], v[128:131], v[196:199], v[108:111]
	v_mfma_f32_16x16x32_bf16 v[100:103], v[136:139], v[196:199], v[100:103]
	v_mfma_f32_16x16x32_bf16 v[76:79], v[128:131], v[206:209], v[76:79]
	v_mfma_f32_16x16x32_bf16 v[72:75], v[136:139], v[206:209], v[72:75]
	v_mfma_f32_16x16x32_bf16 v[124:127], v[132:135], v[184:187], v[124:127]
	v_mfma_f32_16x16x32_bf16 v[120:123], v[140:143], v[184:187], v[120:123]
	v_mfma_f32_16x16x32_bf16 v[116:119], v[132:135], v[192:195], v[116:119]
	v_mfma_f32_16x16x32_bf16 v[112:115], v[140:143], v[192:195], v[112:115]
	v_mfma_f32_16x16x32_bf16 v[108:111], v[132:135], v[200:203], v[108:111]
	v_mfma_f32_16x16x32_bf16 v[100:103], v[140:143], v[200:203], v[100:103]
	v_mfma_f32_16x16x32_bf16 v[76:79], v[132:135], v[210:213], v[76:79]
	v_mfma_f32_16x16x32_bf16 v[72:75], v[140:143], v[210:213], v[72:75]
	v_mfma_f32_16x16x32_bf16 v[104:107], v[164:167], v[180:183], v[104:107]
	v_mfma_f32_16x16x32_bf16 v[96:99], v[172:175], v[180:183], v[96:99]
	v_mfma_f32_16x16x32_bf16 v[92:95], v[164:167], v[188:191], v[92:95]
	v_mfma_f32_16x16x32_bf16 v[88:91], v[172:175], v[188:191], v[88:91]
	v_mfma_f32_16x16x32_bf16 v[84:87], v[164:167], v[196:199], v[84:87]
	v_mfma_f32_16x16x32_bf16 v[80:83], v[172:175], v[196:199], v[80:83]
	v_mfma_f32_16x16x32_bf16 v[68:71], v[164:167], v[206:209], v[68:71]
	v_mfma_f32_16x16x32_bf16 v[64:67], v[172:175], v[206:209], v[64:67]
	v_mfma_f32_16x16x32_bf16 v[104:107], v[168:171], v[184:187], v[104:107]
	v_mfma_f32_16x16x32_bf16 v[96:99], v[176:179], v[184:187], v[96:99]
	v_mfma_f32_16x16x32_bf16 v[92:95], v[168:171], v[192:195], v[92:95]
	v_mfma_f32_16x16x32_bf16 v[88:91], v[176:179], v[192:195], v[88:91]
	v_mfma_f32_16x16x32_bf16 v[84:87], v[168:171], v[200:203], v[84:87]
	v_mfma_f32_16x16x32_bf16 v[80:83], v[176:179], v[200:203], v[80:83]
	v_mfma_f32_16x16x32_bf16 v[68:71], v[168:171], v[210:213], v[68:71]
	v_mfma_f32_16x16x32_bf16 v[64:67], v[176:179], v[210:213], v[64:67]
	s_barrier
	s_setprio 0
	s_add_i32 s3, s3, s19
	v_lshl_add_u64 v[156:157], v[156:157], 0, s[44:45]
	s_mov_b32 m0, s3
	ds_read_b128 v[180:183], v163 offset:49152
	ds_read_b128 v[184:187], v163 offset:50176
	ds_read_b128 v[188:191], v163 offset:51200
	ds_read_b128 v[192:195], v163 offset:52224
	ds_read_b128 v[196:199], v163 offset:53248
	ds_read_b128 v[200:203], v163 offset:54272
	ds_read_b128 v[206:209], v163 offset:55296
	ds_read_b128 v[210:213], v163 offset:56320
	global_load_lds_dwordx4 v[156:157], off
	s_add_i32 m0, s3, 0x2000
	s_add_u32 s16, s72, 0x20800
	v_lshl_add_u64 v[156:157], v[214:215], 0, s[44:45]
	s_addc_u32 s17, s73, 0
	s_add_i32 s3, s33, s19
	global_load_lds_dwordx4 v[156:157], off
	v_lshl_add_u64 v[156:157], s[16:17], 0, v[148:149]
	s_mov_b32 m0, s3
	s_nop 0
	global_load_lds_dwordx4 v[156:157], off
	v_lshl_add_u64 v[156:157], s[16:17], 0, v[144:145]
	s_add_i32 m0, s3, 0x2000
	s_nop 0
	global_load_lds_dwordx4 v[156:157], off
	v_lshl_add_u64 v[156:157], v[216:217], 0, s[46:47]
	s_mov_b32 m0, s83
	s_nop 0
	global_load_lds_dwordx4 v[156:157], off
	v_lshl_add_u64 v[156:157], v[218:219], 0, s[46:47]
	s_mov_b32 m0, s84
	s_nop 0
	global_load_lds_dwordx4 v[156:157], off
	s_waitcnt vmcnt(8)
	s_waitcnt lgkmcnt(0)
	s_setprio 1
	s_barrier
	v_mfma_f32_16x16x32_bf16 v[60:63], v[128:131], v[180:183], v[60:63]
	v_mfma_f32_16x16x32_bf16 v[56:59], v[136:139], v[180:183], v[56:59]
	v_mfma_f32_16x16x32_bf16 v[48:51], v[128:131], v[188:191], v[48:51]
	v_mfma_f32_16x16x32_bf16 v[40:43], v[136:139], v[188:191], v[40:43]
	v_mfma_f32_16x16x32_bf16 v[32:35], v[128:131], v[196:199], v[32:35]
	v_mfma_f32_16x16x32_bf16 v[24:27], v[136:139], v[196:199], v[24:27]
	v_mfma_f32_16x16x32_bf16 v[16:19], v[128:131], v[206:209], v[16:19]
	v_mfma_f32_16x16x32_bf16 v[8:11], v[136:139], v[206:209], v[8:11]
	v_mfma_f32_16x16x32_bf16 v[60:63], v[132:135], v[184:187], v[60:63]
	v_mfma_f32_16x16x32_bf16 v[56:59], v[140:143], v[184:187], v[56:59]
	v_mfma_f32_16x16x32_bf16 v[48:51], v[132:135], v[192:195], v[48:51]
	v_mfma_f32_16x16x32_bf16 v[40:43], v[140:143], v[192:195], v[40:43]
	v_mfma_f32_16x16x32_bf16 v[32:35], v[132:135], v[200:203], v[32:35]
	v_mfma_f32_16x16x32_bf16 v[24:27], v[140:143], v[200:203], v[24:27]
	v_mfma_f32_16x16x32_bf16 v[16:19], v[132:135], v[210:213], v[16:19]
	v_mfma_f32_16x16x32_bf16 v[8:11], v[140:143], v[210:213], v[8:11]
	v_mfma_f32_16x16x32_bf16 v[52:55], v[164:167], v[180:183], v[52:55]
	v_mfma_f32_16x16x32_bf16 v[44:47], v[172:175], v[180:183], v[44:47]
	v_mfma_f32_16x16x32_bf16 v[36:39], v[164:167], v[188:191], v[36:39]
	v_mfma_f32_16x16x32_bf16 v[28:31], v[172:175], v[188:191], v[28:31]
	v_mfma_f32_16x16x32_bf16 v[20:23], v[164:167], v[196:199], v[20:23]
	v_mfma_f32_16x16x32_bf16 v[12:15], v[172:175], v[196:199], v[12:15]
	v_mfma_f32_16x16x32_bf16 v[4:7], v[164:167], v[206:209], v[4:7]
	v_mfma_f32_16x16x32_bf16 v[0:3], v[172:175], v[206:209], v[0:3]
	v_mfma_f32_16x16x32_bf16 v[52:55], v[168:171], v[184:187], v[52:55]
	v_mfma_f32_16x16x32_bf16 v[44:47], v[176:179], v[184:187], v[44:47]
	v_mfma_f32_16x16x32_bf16 v[36:39], v[168:171], v[192:195], v[36:39]
	s_add_i32 vcc_hi, vcc_hi, 2
	v_mfma_f32_16x16x32_bf16 v[28:31], v[176:179], v[192:195], v[28:31]
	s_add_u32 s97, s97, 0x1000
	v_mfma_f32_16x16x32_bf16 v[20:23], v[168:171], v[200:203], v[20:23]
	s_addc_u32 vcc_lo, vcc_lo, 0
	v_mfma_f32_16x16x32_bf16 v[12:15], v[176:179], v[200:203], v[12:15]
	s_add_u32 s70, s70, 0x100
	v_mfma_f32_16x16x32_bf16 v[4:7], v[168:171], v[210:213], v[4:7]
	s_addc_u32 s71, s71, 0
	v_mfma_f32_16x16x32_bf16 v[0:3], v[176:179], v[210:213], v[0:3]
	s_cmp_gt_u32 vcc_hi, 5
	s_barrier
	s_setprio 0
	s_cbranch_scc0 .LBB0_432
	s_and_b64 vcc, exec, s[48:49]
	s_cbranch_vccz .LBB0_435
	s_barrier

.LBB0_513:
	ds_read_b128 v[128:131], v230
	ds_read_b128 v[132:135], v230 offset:1024
	ds_read_b128 v[136:139], v230 offset:2048
	ds_read_b128 v[140:143], v230 offset:3072
	ds_read_b128 v[144:147], v231
	ds_read_b128 v[148:151], v231 offset:1024
	ds_read_b128 v[152:155], v231 offset:2048
	ds_read_b128 v[156:159], v231 offset:3072
	s_add_u32 s3, s56, 0xfff00080
	s_addc_u32 s16, s57, -1
	s_cmp_eq_u32 s82, 60
	s_cselect_b32 s61, s43, s16
	s_cselect_b32 s60, s49, s3
	s_cselect_b32 s59, s41, s81
	s_cselect_b32 s58, s55, s80
	v_lshl_add_u64 v[214:215], s[56:57], 0, v[196:197]
	s_add_i32 m0, s62, 0xc000
	ds_read_b128 v[160:163], v232
	ds_read_b128 v[164:167], v232 offset:1024
	ds_read_b128 v[168:171], v232 offset:2048
	ds_read_b128 v[172:175], v232 offset:3072
	ds_read_b128 v[176:179], v232 offset:4096
	ds_read_b128 v[180:183], v232 offset:5120
	ds_read_b128 v[206:209], v232 offset:6144
	ds_read_b128 v[210:213], v232 offset:7168
	global_load_lds_dwordx4 v[214:215], off
	v_lshl_add_u64 v[214:215], s[56:57], 0, v[198:199]
	s_add_i32 m0, s62, 0xe000
	s_nop 0
	global_load_lds_dwordx4 v[214:215], off
	s_waitcnt vmcnt(8)
	s_waitcnt lgkmcnt(0)
	s_setprio 1
	s_barrier
	v_mfma_f32_16x16x32_bf16 v[124:127], v[128:131], v[160:163], v[124:127]
	v_mfma_f32_16x16x32_bf16 v[120:123], v[136:139], v[160:163], v[120:123]
	v_mfma_f32_16x16x32_bf16 v[108:111], v[128:131], v[168:171], v[108:111]
	v_mfma_f32_16x16x32_bf16 v[104:107], v[136:139], v[168:171], v[104:107]
	v_mfma_f32_16x16x32_bf16 v[92:95], v[128:131], v[176:179], v[92:95]
	v_mfma_f32_16x16x32_bf16 v[88:91], v[136:139], v[176:179], v[88:91]
	v_mfma_f32_16x16x32_bf16 v[76:79], v[128:131], v[206:209], v[76:79]
	v_mfma_f32_16x16x32_bf16 v[72:75], v[136:139], v[206:209], v[72:75]
	v_mfma_f32_16x16x32_bf16 v[124:127], v[132:135], v[164:167], v[124:127]
	v_mfma_f32_16x16x32_bf16 v[120:123], v[140:143], v[164:167], v[120:123]
	v_mfma_f32_16x16x32_bf16 v[108:111], v[132:135], v[172:175], v[108:111]
	v_mfma_f32_16x16x32_bf16 v[104:107], v[140:143], v[172:175], v[104:107]
	v_mfma_f32_16x16x32_bf16 v[92:95], v[132:135], v[180:183], v[92:95]
	v_mfma_f32_16x16x32_bf16 v[88:91], v[140:143], v[180:183], v[88:91]
	v_mfma_f32_16x16x32_bf16 v[76:79], v[132:135], v[210:213], v[76:79]
	v_mfma_f32_16x16x32_bf16 v[72:75], v[140:143], v[210:213], v[72:75]
	v_mfma_f32_16x16x32_bf16 v[116:119], v[144:147], v[160:163], v[116:119]
	v_mfma_f32_16x16x32_bf16 v[112:115], v[152:155], v[160:163], v[112:115]
	v_mfma_f32_16x16x32_bf16 v[100:103], v[144:147], v[168:171], v[100:103]
	v_mfma_f32_16x16x32_bf16 v[96:99], v[152:155], v[168:171], v[96:99]
	v_mfma_f32_16x16x32_bf16 v[84:87], v[144:147], v[176:179], v[84:87]
	v_mfma_f32_16x16x32_bf16 v[80:83], v[152:155], v[176:179], v[80:83]
	v_mfma_f32_16x16x32_bf16 v[68:71], v[144:147], v[206:209], v[68:71]
	v_mfma_f32_16x16x32_bf16 v[64:67], v[152:155], v[206:209], v[64:67]
	v_mfma_f32_16x16x32_bf16 v[116:119], v[148:151], v[164:167], v[116:119]
	v_mfma_f32_16x16x32_bf16 v[112:115], v[156:159], v[164:167], v[112:115]
	v_mfma_f32_16x16x32_bf16 v[100:103], v[148:151], v[172:175], v[100:103]
	v_mfma_f32_16x16x32_bf16 v[96:99], v[156:159], v[172:175], v[96:99]
	v_mfma_f32_16x16x32_bf16 v[84:87], v[148:151], v[180:183], v[84:87]
	v_mfma_f32_16x16x32_bf16 v[80:83], v[156:159], v[180:183], v[80:83]
	v_mfma_f32_16x16x32_bf16 v[68:71], v[148:151], v[210:213], v[68:71]
	v_mfma_f32_16x16x32_bf16 v[64:67], v[156:159], v[210:213], v[64:67]
	s_barrier
	s_setprio 0
	s_add_i32 s3, s75, s19
	v_lshl_add_u64 v[214:215], s[58:59], 0, v[186:187]
	s_mov_b32 m0, s3
	ds_read_b128 v[160:163], v232 offset:16384
	ds_read_b128 v[164:167], v232 offset:17408
	ds_read_b128 v[168:171], v232 offset:18432
	ds_read_b128 v[172:175], v232 offset:19456
	ds_read_b128 v[176:179], v232 offset:20480
	ds_read_b128 v[180:183], v232 offset:21504
	ds_read_b128 v[206:209], v232 offset:22528
	ds_read_b128 v[210:213], v232 offset:23552
	global_load_lds_dwordx4 v[214:215], off
	s_add_i32 m0, s3, 0x2000
	s_add_u32 s16, s58, 0x100000
	v_lshl_add_u64 v[216:217], s[58:59], 0, v[190:191]
	s_addc_u32 s17, s59, 0
	s_add_i32 s3, s76, s19
	global_load_lds_dwordx4 v[216:217], off
	v_lshl_add_u64 v[218:219], s[16:17], 0, v[186:187]
	s_mov_b32 m0, s3
	v_lshl_add_u64 v[220:221], s[60:61], 0, v[188:189]
	global_load_lds_dwordx4 v[218:219], off
	v_lshl_add_u64 v[218:219], s[16:17], 0, v[190:191]
	s_add_i32 m0, s3, 0x2000
	s_nop 0
	global_load_lds_dwordx4 v[218:219], off
	v_lshl_add_u64 v[218:219], s[60:61], 0, v[184:185]
	s_mov_b32 m0, s62
	s_nop 0
	global_load_lds_dwordx4 v[218:219], off
	s_mov_b32 m0, s63
	s_nop 0
	global_load_lds_dwordx4 v[220:221], off
	s_waitcnt vmcnt(8)
	s_waitcnt lgkmcnt(0)
	s_setprio 1
	s_barrier
	v_mfma_f32_16x16x32_bf16 v[60:63], v[128:131], v[160:163], v[60:63]
	v_mfma_f32_16x16x32_bf16 v[56:59], v[136:139], v[160:163], v[56:59]
	v_mfma_f32_16x16x32_bf16 v[44:47], v[128:131], v[168:171], v[44:47]
	v_mfma_f32_16x16x32_bf16 v[40:43], v[136:139], v[168:171], v[40:43]
	v_mfma_f32_16x16x32_bf16 v[28:31], v[128:131], v[176:179], v[28:31]
	v_mfma_f32_16x16x32_bf16 v[24:27], v[136:139], v[176:179], v[24:27]
	v_mfma_f32_16x16x32_bf16 v[12:15], v[128:131], v[206:209], v[12:15]
	v_mfma_f32_16x16x32_bf16 v[8:11], v[136:139], v[206:209], v[8:11]
	v_mfma_f32_16x16x32_bf16 v[60:63], v[132:135], v[164:167], v[60:63]
	v_mfma_f32_16x16x32_bf16 v[56:59], v[140:143], v[164:167], v[56:59]
	v_mfma_f32_16x16x32_bf16 v[44:47], v[132:135], v[172:175], v[44:47]
	v_mfma_f32_16x16x32_bf16 v[40:43], v[140:143], v[172:175], v[40:43]
	v_mfma_f32_16x16x32_bf16 v[28:31], v[132:135], v[180:183], v[28:31]
	v_mfma_f32_16x16x32_bf16 v[24:27], v[140:143], v[180:183], v[24:27]
	v_mfma_f32_16x16x32_bf16 v[12:15], v[132:135], v[210:213], v[12:15]
	v_mfma_f32_16x16x32_bf16 v[8:11], v[140:143], v[210:213], v[8:11]
	v_mfma_f32_16x16x32_bf16 v[52:55], v[144:147], v[160:163], v[52:55]
	v_mfma_f32_16x16x32_bf16 v[48:51], v[152:155], v[160:163], v[48:51]
	v_mfma_f32_16x16x32_bf16 v[36:39], v[144:147], v[168:171], v[36:39]
	v_mfma_f32_16x16x32_bf16 v[32:35], v[152:155], v[168:171], v[32:35]
	v_mfma_f32_16x16x32_bf16 v[20:23], v[144:147], v[176:179], v[20:23]
	v_mfma_f32_16x16x32_bf16 v[16:19], v[152:155], v[176:179], v[16:19]
	v_mfma_f32_16x16x32_bf16 v[4:7], v[144:147], v[206:209], v[4:7]
	v_mfma_f32_16x16x32_bf16 v[0:3], v[152:155], v[206:209], v[0:3]
	v_mfma_f32_16x16x32_bf16 v[52:55], v[148:151], v[164:167], v[52:55]
	v_mfma_f32_16x16x32_bf16 v[48:51], v[156:159], v[164:167], v[48:51]
	v_mfma_f32_16x16x32_bf16 v[36:39], v[148:151], v[172:175], v[36:39]
	v_mfma_f32_16x16x32_bf16 v[32:35], v[156:159], v[172:175], v[32:35]
	v_mfma_f32_16x16x32_bf16 v[20:23], v[148:151], v[180:183], v[20:23]
	v_mfma_f32_16x16x32_bf16 v[16:19], v[156:159], v[180:183], v[16:19]
	v_mfma_f32_16x16x32_bf16 v[4:7], v[148:151], v[210:213], v[4:7]
	v_mfma_f32_16x16x32_bf16 v[0:3], v[156:159], v[210:213], v[0:3]
	s_barrier
	s_setprio 0
	s_add_i32 s3, 0, 0x18000
	s_add_i32 s33, 0, 0x1c000
	v_add_u32_e32 v140, s3, v229
	v_add_u32_e32 v156, s33, v229
	ds_read_b128 v[128:131], v140
	ds_read_b128 v[132:135], v140 offset:1024
	ds_read_b128 v[136:139], v140 offset:2048
	ds_read_b128 v[140:143], v140 offset:3072
	ds_read_b128 v[144:147], v156
	ds_read_b128 v[148:151], v156 offset:1024
	ds_read_b128 v[152:155], v156 offset:2048
	ds_read_b128 v[156:159], v156 offset:3072
	s_add_u32 s16, s60, 0x100000
	s_addc_u32 s17, s61, 0
	s_mov_b32 m0, s64
	v_lshl_add_u64 v[222:223], s[16:17], 0, v[184:185]
	ds_read_b128 v[160:163], v232 offset:32768
	ds_read_b128 v[164:167], v232 offset:33792
	ds_read_b128 v[168:171], v232 offset:34816
	ds_read_b128 v[172:175], v232 offset:35840
	ds_read_b128 v[176:179], v232 offset:36864
	ds_read_b128 v[180:183], v232 offset:37888
	ds_read_b128 v[206:209], v232 offset:38912
	ds_read_b128 v[210:213], v232 offset:39936
	global_load_lds_dwordx4 v[222:223], off
	v_lshl_add_u64 v[222:223], s[16:17], 0, v[188:189]
	s_mov_b32 m0, s65
	s_nop 0
	global_load_lds_dwordx4 v[222:223], off
	s_waitcnt vmcnt(8)
	s_waitcnt lgkmcnt(0)
	s_setprio 1
	s_barrier
	v_mfma_f32_16x16x32_bf16 v[124:127], v[128:131], v[160:163], v[124:127]
	v_mfma_f32_16x16x32_bf16 v[120:123], v[136:139], v[160:163], v[120:123]
	v_mfma_f32_16x16x32_bf16 v[108:111], v[128:131], v[168:171], v[108:111]
	v_mfma_f32_16x16x32_bf16 v[104:107], v[136:139], v[168:171], v[104:107]
	v_mfma_f32_16x16x32_bf16 v[92:95], v[128:131], v[176:179], v[92:95]
	v_mfma_f32_16x16x32_bf16 v[88:91], v[136:139], v[176:179], v[88:91]
	v_mfma_f32_16x16x32_bf16 v[76:79], v[128:131], v[206:209], v[76:79]
	v_mfma_f32_16x16x32_bf16 v[72:75], v[136:139], v[206:209], v[72:75]
	v_mfma_f32_16x16x32_bf16 v[124:127], v[132:135], v[164:167], v[124:127]
	v_mfma_f32_16x16x32_bf16 v[120:123], v[140:143], v[164:167], v[120:123]
	v_mfma_f32_16x16x32_bf16 v[108:111], v[132:135], v[172:175], v[108:111]
	v_mfma_f32_16x16x32_bf16 v[104:107], v[140:143], v[172:175], v[104:107]
	v_mfma_f32_16x16x32_bf16 v[92:95], v[132:135], v[180:183], v[92:95]
	v_mfma_f32_16x16x32_bf16 v[88:91], v[140:143], v[180:183], v[88:91]
	v_mfma_f32_16x16x32_bf16 v[76:79], v[132:135], v[210:213], v[76:79]
	v_mfma_f32_16x16x32_bf16 v[72:75], v[140:143], v[210:213], v[72:75]
	v_mfma_f32_16x16x32_bf16 v[116:119], v[144:147], v[160:163], v[116:119]
	v_mfma_f32_16x16x32_bf16 v[112:115], v[152:155], v[160:163], v[112:115]
	v_mfma_f32_16x16x32_bf16 v[100:103], v[144:147], v[168:171], v[100:103]
	v_mfma_f32_16x16x32_bf16 v[96:99], v[152:155], v[168:171], v[96:99]
	v_mfma_f32_16x16x32_bf16 v[84:87], v[144:147], v[176:179], v[84:87]
	v_mfma_f32_16x16x32_bf16 v[80:83], v[152:155], v[176:179], v[80:83]
	v_mfma_f32_16x16x32_bf16 v[68:71], v[144:147], v[206:209], v[68:71]
	v_mfma_f32_16x16x32_bf16 v[64:67], v[152:155], v[206:209], v[64:67]
	v_mfma_f32_16x16x32_bf16 v[116:119], v[148:151], v[164:167], v[116:119]
	v_mfma_f32_16x16x32_bf16 v[112:115], v[156:159], v[164:167], v[112:115]
	v_mfma_f32_16x16x32_bf16 v[100:103], v[148:151], v[172:175], v[100:103]
	v_mfma_f32_16x16x32_bf16 v[96:99], v[156:159], v[172:175], v[96:99]
	v_mfma_f32_16x16x32_bf16 v[84:87], v[148:151], v[180:183], v[84:87]
	v_mfma_f32_16x16x32_bf16 v[80:83], v[156:159], v[180:183], v[80:83]
	v_mfma_f32_16x16x32_bf16 v[68:71], v[148:151], v[210:213], v[68:71]
	v_mfma_f32_16x16x32_bf16 v[64:67], v[156:159], v[210:213], v[64:67]
	s_barrier
	s_setprio 0
	s_add_i32 s3, s3, s19
	v_lshl_add_u64 v[214:215], v[214:215], 0, s[14:15]
	s_mov_b32 m0, s3
	ds_read_b128 v[160:163], v232 offset:49152
	ds_read_b128 v[164:167], v232 offset:50176
	ds_read_b128 v[168:171], v232 offset:51200
	ds_read_b128 v[172:175], v232 offset:52224
	ds_read_b128 v[176:179], v232 offset:53248
	ds_read_b128 v[180:183], v232 offset:54272
	ds_read_b128 v[206:209], v232 offset:55296
	ds_read_b128 v[210:213], v232 offset:56320
	global_load_lds_dwordx4 v[214:215], off
	s_add_i32 m0, s3, 0x2000
	s_add_u32 s16, s58, 0x100800
	v_lshl_add_u64 v[214:215], v[216:217], 0, s[14:15]
	s_addc_u32 s17, s59, 0
	s_add_i32 s3, s33, s19
	global_load_lds_dwordx4 v[214:215], off
	v_lshl_add_u64 v[214:215], s[16:17], 0, v[186:187]
	s_mov_b32 m0, s3
	s_nop 0
	global_load_lds_dwordx4 v[214:215], off
	v_lshl_add_u64 v[214:215], s[16:17], 0, v[190:191]
	s_add_i32 m0, s3, 0x2000
	s_nop 0
	global_load_lds_dwordx4 v[214:215], off
	v_lshl_add_u64 v[214:215], v[218:219], 0, s[36:37]
	s_mov_b32 m0, s70
	s_nop 0
	global_load_lds_dwordx4 v[214:215], off
	v_lshl_add_u64 v[214:215], v[220:221], 0, s[36:37]
	s_mov_b32 m0, s71
	s_nop 0
	global_load_lds_dwordx4 v[214:215], off
	s_waitcnt vmcnt(8)
	s_waitcnt lgkmcnt(0)
	s_setprio 1
	s_barrier
	v_mfma_f32_16x16x32_bf16 v[60:63], v[128:131], v[160:163], v[60:63]
	v_mfma_f32_16x16x32_bf16 v[56:59], v[136:139], v[160:163], v[56:59]
	v_mfma_f32_16x16x32_bf16 v[44:47], v[128:131], v[168:171], v[44:47]
	v_mfma_f32_16x16x32_bf16 v[40:43], v[136:139], v[168:171], v[40:43]
	v_mfma_f32_16x16x32_bf16 v[28:31], v[128:131], v[176:179], v[28:31]
	v_mfma_f32_16x16x32_bf16 v[24:27], v[136:139], v[176:179], v[24:27]
	v_mfma_f32_16x16x32_bf16 v[12:15], v[128:131], v[206:209], v[12:15]
	v_mfma_f32_16x16x32_bf16 v[8:11], v[136:139], v[206:209], v[8:11]
	v_mfma_f32_16x16x32_bf16 v[60:63], v[132:135], v[164:167], v[60:63]
	v_mfma_f32_16x16x32_bf16 v[56:59], v[140:143], v[164:167], v[56:59]
	v_mfma_f32_16x16x32_bf16 v[44:47], v[132:135], v[172:175], v[44:47]
	v_mfma_f32_16x16x32_bf16 v[40:43], v[140:143], v[172:175], v[40:43]
	v_mfma_f32_16x16x32_bf16 v[28:31], v[132:135], v[180:183], v[28:31]
	v_mfma_f32_16x16x32_bf16 v[24:27], v[140:143], v[180:183], v[24:27]
	v_mfma_f32_16x16x32_bf16 v[12:15], v[132:135], v[210:213], v[12:15]
	v_mfma_f32_16x16x32_bf16 v[8:11], v[140:143], v[210:213], v[8:11]
	v_mfma_f32_16x16x32_bf16 v[52:55], v[144:147], v[160:163], v[52:55]
	v_mfma_f32_16x16x32_bf16 v[48:51], v[152:155], v[160:163], v[48:51]
	v_mfma_f32_16x16x32_bf16 v[36:39], v[144:147], v[168:171], v[36:39]
	v_mfma_f32_16x16x32_bf16 v[32:35], v[152:155], v[168:171], v[32:35]
	v_mfma_f32_16x16x32_bf16 v[20:23], v[144:147], v[176:179], v[20:23]
	v_mfma_f32_16x16x32_bf16 v[16:19], v[152:155], v[176:179], v[16:19]
	v_mfma_f32_16x16x32_bf16 v[4:7], v[144:147], v[206:209], v[4:7]
	v_mfma_f32_16x16x32_bf16 v[0:3], v[152:155], v[206:209], v[0:3]
	v_mfma_f32_16x16x32_bf16 v[52:55], v[148:151], v[164:167], v[52:55]
	v_mfma_f32_16x16x32_bf16 v[48:51], v[156:159], v[164:167], v[48:51]
	v_mfma_f32_16x16x32_bf16 v[36:39], v[148:151], v[172:175], v[36:39]
	s_add_i32 s82, s82, 2
	v_mfma_f32_16x16x32_bf16 v[32:35], v[156:159], v[172:175], v[32:35]
	s_add_u32 s80, s80, 0x1000
	v_mfma_f32_16x16x32_bf16 v[20:23], v[148:151], v[180:183], v[20:23]
	s_addc_u32 s81, s81, 0
	v_mfma_f32_16x16x32_bf16 v[16:19], v[156:159], v[180:183], v[16:19]
	s_add_u32 s56, s56, 0x100
	v_mfma_f32_16x16x32_bf16 v[4:7], v[148:151], v[210:213], v[4:7]
	s_addc_u32 s57, s57, 0
	v_mfma_f32_16x16x32_bf16 v[0:3], v[156:159], v[210:213], v[0:3]
	s_cmp_gt_u32 s82, 61
	s_barrier
	s_setprio 0
	s_cbranch_scc0 .LBB0_513
	s_and_b64 vcc, exec, s[38:39]
	s_cbranch_vccz .LBB0_516
	s_barrier

.LBB0_639:
	ds_read_b128 v[52:55], v188
	ds_read_b128 v[56:59], v188 offset:1024
	ds_read_b128 v[60:63], v188 offset:2048
	ds_read_b128 v[64:67], v188 offset:3072
	ds_read_b128 v[72:75], v189
	ds_read_b128 v[76:79], v189 offset:1024
	ds_read_b128 v[80:83], v189 offset:2048
	ds_read_b128 v[84:87], v189 offset:3072
	s_add_u32 s60, s14, 0x1000
	s_addc_u32 s61, s15, 0
	s_cmp_eq_u32 s93, 60
	s_cselect_b32 s65, s11, s61
	s_cselect_b32 s64, s13, s60
	s_cselect_b32 s63, s53, s91
	s_cselect_b32 s62, s55, s90
	v_lshl_add_u64 v[224:225], s[14:15], 0, v[172:173]
	s_add_i32 m0, s66, 0xc000
	ds_read_b128 v[180:183], v190
	ds_read_b128 v[196:199], v190 offset:1024
	ds_read_b128 v[200:203], v190 offset:2048
	ds_read_b128 v[204:207], v190 offset:3072
	ds_read_b128 v[208:211], v190 offset:4096
	ds_read_b128 v[212:215], v190 offset:5120
	ds_read_b128 v[216:219], v190 offset:6144
	ds_read_b128 v[220:223], v190 offset:7168
	global_load_lds_dwordx4 v[224:225], off
	v_lshl_add_u64 v[224:225], s[14:15], 0, v[174:175]
	s_add_i32 m0, s66, 0xe000
	s_nop 0
	global_load_lds_dwordx4 v[224:225], off
	s_waitcnt vmcnt(8)
	s_waitcnt lgkmcnt(0)
	s_setprio 1
	s_barrier
	v_mfma_f32_16x16x32_bf16 v[156:159], v[52:55], v[180:183], v[156:159]
	v_mfma_f32_16x16x32_bf16 v[152:155], v[60:63], v[180:183], v[152:155]
	v_mfma_f32_16x16x32_bf16 v[140:143], v[52:55], v[200:203], v[140:143]
	v_mfma_f32_16x16x32_bf16 v[136:139], v[60:63], v[200:203], v[136:139]
	v_mfma_f32_16x16x32_bf16 v[124:127], v[52:55], v[208:211], v[124:127]
	v_mfma_f32_16x16x32_bf16 v[120:123], v[60:63], v[208:211], v[120:123]
	v_mfma_f32_16x16x32_bf16 v[108:111], v[52:55], v[216:219], v[108:111]
	v_mfma_f32_16x16x32_bf16 v[104:107], v[60:63], v[216:219], v[104:107]
	v_mfma_f32_16x16x32_bf16 v[156:159], v[56:59], v[196:199], v[156:159]
	v_mfma_f32_16x16x32_bf16 v[152:155], v[64:67], v[196:199], v[152:155]
	v_mfma_f32_16x16x32_bf16 v[140:143], v[56:59], v[204:207], v[140:143]
	v_mfma_f32_16x16x32_bf16 v[136:139], v[64:67], v[204:207], v[136:139]
	v_mfma_f32_16x16x32_bf16 v[124:127], v[56:59], v[212:215], v[124:127]
	v_mfma_f32_16x16x32_bf16 v[120:123], v[64:67], v[212:215], v[120:123]
	v_mfma_f32_16x16x32_bf16 v[108:111], v[56:59], v[220:223], v[108:111]
	v_mfma_f32_16x16x32_bf16 v[104:107], v[64:67], v[220:223], v[104:107]
	v_mfma_f32_16x16x32_bf16 v[144:147], v[72:75], v[180:183], v[144:147]
	v_mfma_f32_16x16x32_bf16 v[148:151], v[80:83], v[180:183], v[148:151]
	v_mfma_f32_16x16x32_bf16 v[128:131], v[72:75], v[200:203], v[128:131]
	v_mfma_f32_16x16x32_bf16 v[132:135], v[80:83], v[200:203], v[132:135]
	v_mfma_f32_16x16x32_bf16 v[112:115], v[72:75], v[208:211], v[112:115]
	v_mfma_f32_16x16x32_bf16 v[116:119], v[80:83], v[208:211], v[116:119]
	v_mfma_f32_16x16x32_bf16 v[96:99], v[72:75], v[216:219], v[96:99]
	v_mfma_f32_16x16x32_bf16 v[100:103], v[80:83], v[216:219], v[100:103]
	v_mfma_f32_16x16x32_bf16 v[144:147], v[76:79], v[196:199], v[144:147]
	v_mfma_f32_16x16x32_bf16 v[148:151], v[84:87], v[196:199], v[148:151]
	v_mfma_f32_16x16x32_bf16 v[128:131], v[76:79], v[204:207], v[128:131]
	v_mfma_f32_16x16x32_bf16 v[132:135], v[84:87], v[204:207], v[132:135]
	v_mfma_f32_16x16x32_bf16 v[112:115], v[76:79], v[212:215], v[112:115]
	v_mfma_f32_16x16x32_bf16 v[116:119], v[84:87], v[212:215], v[116:119]
	v_mfma_f32_16x16x32_bf16 v[96:99], v[76:79], v[220:223], v[96:99]
	v_mfma_f32_16x16x32_bf16 v[100:103], v[84:87], v[220:223], v[100:103]
	s_barrier
	s_setprio 0
	s_add_i32 s3, s80, s19
	v_lshl_add_u64 v[224:225], s[62:63], 0, v[162:163]
	s_mov_b32 m0, s3
	ds_read_b128 v[180:183], v190 offset:16384
	ds_read_b128 v[196:199], v190 offset:17408
	ds_read_b128 v[200:203], v190 offset:18432
	ds_read_b128 v[204:207], v190 offset:19456
	ds_read_b128 v[208:211], v190 offset:20480
	ds_read_b128 v[212:215], v190 offset:21504
	ds_read_b128 v[216:219], v190 offset:22528
	ds_read_b128 v[220:223], v190 offset:23552
	global_load_lds_dwordx4 v[224:225], off
	s_add_i32 m0, s3, 0x2000
	s_add_u32 s14, s62, 0x100000
	v_lshl_add_u64 v[228:229], s[62:63], 0, v[166:167]
	s_addc_u32 s15, s63, 0
	s_add_i32 s3, s81, s19
	global_load_lds_dwordx4 v[228:229], off
	v_lshl_add_u64 v[230:231], s[14:15], 0, v[162:163]
	s_mov_b32 m0, s3
	v_lshl_add_u64 v[232:233], s[64:65], 0, v[164:165]
	global_load_lds_dwordx4 v[230:231], off
	v_lshl_add_u64 v[230:231], s[14:15], 0, v[166:167]
	s_add_i32 m0, s3, 0x2000
	s_nop 0
	global_load_lds_dwordx4 v[230:231], off
	v_lshl_add_u64 v[230:231], s[64:65], 0, v[160:161]
	s_mov_b32 m0, s66
	s_nop 0
	global_load_lds_dwordx4 v[230:231], off
	s_mov_b32 m0, s67
	s_nop 0
	global_load_lds_dwordx4 v[232:233], off
	s_waitcnt vmcnt(8)
	s_waitcnt lgkmcnt(0)
	s_setprio 1
	s_barrier
	v_mfma_f32_16x16x32_bf16 v[92:95], v[52:55], v[180:183], v[92:95]
	v_mfma_f32_16x16x32_bf16 v[88:91], v[60:63], v[180:183], v[88:91]
	v_mfma_f32_16x16x32_bf16 v[44:47], v[52:55], v[200:203], v[44:47]
	v_mfma_f32_16x16x32_bf16 v[40:43], v[60:63], v[200:203], v[40:43]
	v_mfma_f32_16x16x32_bf16 v[28:31], v[52:55], v[208:211], v[28:31]
	v_mfma_f32_16x16x32_bf16 v[24:27], v[60:63], v[208:211], v[24:27]
	v_mfma_f32_16x16x32_bf16 v[12:15], v[52:55], v[216:219], v[12:15]
	v_mfma_f32_16x16x32_bf16 v[8:11], v[60:63], v[216:219], v[8:11]
	v_mfma_f32_16x16x32_bf16 v[92:95], v[56:59], v[196:199], v[92:95]
	v_mfma_f32_16x16x32_bf16 v[88:91], v[64:67], v[196:199], v[88:91]
	v_mfma_f32_16x16x32_bf16 v[44:47], v[56:59], v[204:207], v[44:47]
	v_mfma_f32_16x16x32_bf16 v[40:43], v[64:67], v[204:207], v[40:43]
	v_mfma_f32_16x16x32_bf16 v[28:31], v[56:59], v[212:215], v[28:31]
	v_mfma_f32_16x16x32_bf16 v[24:27], v[64:67], v[212:215], v[24:27]
	v_mfma_f32_16x16x32_bf16 v[12:15], v[56:59], v[220:223], v[12:15]
	v_mfma_f32_16x16x32_bf16 v[8:11], v[64:67], v[220:223], v[8:11]
	v_mfma_f32_16x16x32_bf16 v[48:51], v[72:75], v[180:183], v[48:51]
	v_mfma_f32_16x16x32_bf16 v[32:35], v[72:75], v[200:203], v[32:35]
	v_mfma_f32_16x16x32_bf16 v[36:39], v[80:83], v[200:203], v[36:39]
	v_mfma_f32_16x16x32_bf16 v[16:19], v[72:75], v[208:211], v[16:19]
	v_mfma_f32_16x16x32_bf16 v[20:23], v[80:83], v[208:211], v[20:23]
	v_mfma_f32_16x16x32_bf16 v[0:3], v[72:75], v[216:219], v[0:3]
	v_mfma_f32_16x16x32_bf16 v[4:7], v[80:83], v[216:219], v[4:7]
	v_mfma_f32_16x16x32_bf16 v[48:51], v[76:79], v[196:199], v[48:51]
	v_mfma_f32_16x16x32_bf16 v[52:55], v[80:83], v[180:183], v[68:71]
	v_mfma_f32_16x16x32_bf16 v[32:35], v[76:79], v[204:207], v[32:35]
	v_mfma_f32_16x16x32_bf16 v[36:39], v[84:87], v[204:207], v[36:39]
	v_mfma_f32_16x16x32_bf16 v[16:19], v[76:79], v[212:215], v[16:19]
	v_mfma_f32_16x16x32_bf16 v[20:23], v[84:87], v[212:215], v[20:23]
	v_mfma_f32_16x16x32_bf16 v[0:3], v[76:79], v[220:223], v[0:3]
	v_mfma_f32_16x16x32_bf16 v[4:7], v[84:87], v[220:223], v[4:7]
	v_mfma_f32_16x16x32_bf16 v[52:55], v[84:87], v[196:199], v[52:55]
	s_barrier
	s_setprio 0
	s_add_i32 s3, 0, 0x18000
	s_add_i32 s16, 0, 0x1c000
	v_add_u32_e32 v68, s3, v171
	v_add_u32_e32 v84, s16, v171
	ds_read_b128 v[56:59], v68
	ds_read_b128 v[60:63], v68 offset:1024
	ds_read_b128 v[64:67], v68 offset:2048
	ds_read_b128 v[68:71], v68 offset:3072
	ds_read_b128 v[72:75], v84
	ds_read_b128 v[76:79], v84 offset:1024
	ds_read_b128 v[80:83], v84 offset:2048
	ds_read_b128 v[84:87], v84 offset:3072
	s_add_u32 s14, s64, 0x80000
	s_addc_u32 s15, s65, 0
	s_mov_b32 m0, s70
	v_lshl_add_u64 v[234:235], s[14:15], 0, v[160:161]
	ds_read_b128 v[180:183], v190 offset:32768
	ds_read_b128 v[196:199], v190 offset:33792
	ds_read_b128 v[200:203], v190 offset:34816
	ds_read_b128 v[204:207], v190 offset:35840
	ds_read_b128 v[208:211], v190 offset:36864
	ds_read_b128 v[212:215], v190 offset:37888
	ds_read_b128 v[216:219], v190 offset:38912
	ds_read_b128 v[220:223], v190 offset:39936
	global_load_lds_dwordx4 v[234:235], off
	v_lshl_add_u64 v[234:235], s[14:15], 0, v[164:165]
	s_mov_b32 m0, s71
	s_nop 0
	global_load_lds_dwordx4 v[234:235], off
	s_waitcnt vmcnt(8)
	s_waitcnt lgkmcnt(0)
	s_setprio 1
	s_barrier
	v_mfma_f32_16x16x32_bf16 v[156:159], v[56:59], v[180:183], v[156:159]
	v_mfma_f32_16x16x32_bf16 v[152:155], v[64:67], v[180:183], v[152:155]
	v_mfma_f32_16x16x32_bf16 v[140:143], v[56:59], v[200:203], v[140:143]
	v_mfma_f32_16x16x32_bf16 v[136:139], v[64:67], v[200:203], v[136:139]
	v_mfma_f32_16x16x32_bf16 v[124:127], v[56:59], v[208:211], v[124:127]
	v_mfma_f32_16x16x32_bf16 v[120:123], v[64:67], v[208:211], v[120:123]
	v_mfma_f32_16x16x32_bf16 v[108:111], v[56:59], v[216:219], v[108:111]
	v_mfma_f32_16x16x32_bf16 v[104:107], v[64:67], v[216:219], v[104:107]
	v_mfma_f32_16x16x32_bf16 v[156:159], v[60:63], v[196:199], v[156:159]
	v_mfma_f32_16x16x32_bf16 v[152:155], v[68:71], v[196:199], v[152:155]
	v_mfma_f32_16x16x32_bf16 v[140:143], v[60:63], v[204:207], v[140:143]
	v_mfma_f32_16x16x32_bf16 v[136:139], v[68:71], v[204:207], v[136:139]
	v_mfma_f32_16x16x32_bf16 v[124:127], v[60:63], v[212:215], v[124:127]
	v_mfma_f32_16x16x32_bf16 v[120:123], v[68:71], v[212:215], v[120:123]
	v_mfma_f32_16x16x32_bf16 v[108:111], v[60:63], v[220:223], v[108:111]
	v_mfma_f32_16x16x32_bf16 v[104:107], v[68:71], v[220:223], v[104:107]
	v_mfma_f32_16x16x32_bf16 v[144:147], v[72:75], v[180:183], v[144:147]
	v_mfma_f32_16x16x32_bf16 v[148:151], v[80:83], v[180:183], v[148:151]
	v_mfma_f32_16x16x32_bf16 v[128:131], v[72:75], v[200:203], v[128:131]
	v_mfma_f32_16x16x32_bf16 v[132:135], v[80:83], v[200:203], v[132:135]
	v_mfma_f32_16x16x32_bf16 v[112:115], v[72:75], v[208:211], v[112:115]
	v_mfma_f32_16x16x32_bf16 v[116:119], v[80:83], v[208:211], v[116:119]
	v_mfma_f32_16x16x32_bf16 v[96:99], v[72:75], v[216:219], v[96:99]
	v_mfma_f32_16x16x32_bf16 v[100:103], v[80:83], v[216:219], v[100:103]
	v_mfma_f32_16x16x32_bf16 v[144:147], v[76:79], v[196:199], v[144:147]
	v_mfma_f32_16x16x32_bf16 v[148:151], v[84:87], v[196:199], v[148:151]
	v_mfma_f32_16x16x32_bf16 v[128:131], v[76:79], v[204:207], v[128:131]
	v_mfma_f32_16x16x32_bf16 v[132:135], v[84:87], v[204:207], v[132:135]
	v_mfma_f32_16x16x32_bf16 v[112:115], v[76:79], v[212:215], v[112:115]
	v_mfma_f32_16x16x32_bf16 v[116:119], v[84:87], v[212:215], v[116:119]
	v_mfma_f32_16x16x32_bf16 v[96:99], v[76:79], v[220:223], v[96:99]
	v_mfma_f32_16x16x32_bf16 v[100:103], v[84:87], v[220:223], v[100:103]
	s_barrier
	s_setprio 0
	s_add_i32 s3, s3, s19
	v_lshl_add_u64 v[224:225], v[224:225], 0, s[40:41]
	s_mov_b32 m0, s3
	ds_read_b128 v[180:183], v190 offset:49152
	ds_read_b128 v[196:199], v190 offset:50176
	ds_read_b128 v[200:203], v190 offset:51200
	ds_read_b128 v[204:207], v190 offset:52224
	ds_read_b128 v[208:211], v190 offset:53248
	ds_read_b128 v[212:215], v190 offset:54272
	ds_read_b128 v[216:219], v190 offset:55296
	ds_read_b128 v[220:223], v190 offset:56320
	global_load_lds_dwordx4 v[224:225], off
	s_add_i32 m0, s3, 0x2000
	s_add_u32 s14, s62, 0x100800
	v_lshl_add_u64 v[224:225], v[228:229], 0, s[40:41]
	s_addc_u32 s15, s63, 0
	s_add_i32 s3, s16, s19
	global_load_lds_dwordx4 v[224:225], off
	v_lshl_add_u64 v[224:225], s[14:15], 0, v[162:163]
	s_mov_b32 m0, s3
	s_nop 0
	global_load_lds_dwordx4 v[224:225], off
	v_lshl_add_u64 v[224:225], s[14:15], 0, v[166:167]
	s_add_i32 m0, s3, 0x2000
	s_nop 0
	global_load_lds_dwordx4 v[224:225], off
	v_lshl_add_u64 v[224:225], v[230:231], 0, s[40:41]
	s_mov_b32 m0, s75
	s_nop 0
	global_load_lds_dwordx4 v[224:225], off
	v_lshl_add_u64 v[224:225], v[232:233], 0, s[40:41]
	s_mov_b32 m0, s76
	s_nop 0
	global_load_lds_dwordx4 v[224:225], off
	s_waitcnt vmcnt(8)
	s_waitcnt lgkmcnt(0)
	s_setprio 1
	s_barrier
	v_mfma_f32_16x16x32_bf16 v[92:95], v[56:59], v[180:183], v[92:95]
	v_mfma_f32_16x16x32_bf16 v[88:91], v[64:67], v[180:183], v[88:91]
	v_mfma_f32_16x16x32_bf16 v[44:47], v[56:59], v[200:203], v[44:47]
	v_mfma_f32_16x16x32_bf16 v[40:43], v[64:67], v[200:203], v[40:43]
	v_mfma_f32_16x16x32_bf16 v[28:31], v[56:59], v[208:211], v[28:31]
	v_mfma_f32_16x16x32_bf16 v[24:27], v[64:67], v[208:211], v[24:27]
	v_mfma_f32_16x16x32_bf16 v[12:15], v[56:59], v[216:219], v[12:15]
	v_mfma_f32_16x16x32_bf16 v[8:11], v[64:67], v[216:219], v[8:11]
	v_mfma_f32_16x16x32_bf16 v[92:95], v[60:63], v[196:199], v[92:95]
	v_mfma_f32_16x16x32_bf16 v[88:91], v[68:71], v[196:199], v[88:91]
	v_mfma_f32_16x16x32_bf16 v[44:47], v[60:63], v[204:207], v[44:47]
	v_mfma_f32_16x16x32_bf16 v[40:43], v[68:71], v[204:207], v[40:43]
	v_mfma_f32_16x16x32_bf16 v[28:31], v[60:63], v[212:215], v[28:31]
	v_mfma_f32_16x16x32_bf16 v[24:27], v[68:71], v[212:215], v[24:27]
	v_mfma_f32_16x16x32_bf16 v[12:15], v[60:63], v[220:223], v[12:15]
	v_mfma_f32_16x16x32_bf16 v[8:11], v[68:71], v[220:223], v[8:11]
	v_mfma_f32_16x16x32_bf16 v[48:51], v[72:75], v[180:183], v[48:51]
	v_mfma_f32_16x16x32_bf16 v[52:55], v[80:83], v[180:183], v[52:55]
	v_mfma_f32_16x16x32_bf16 v[32:35], v[72:75], v[200:203], v[32:35]
	v_mfma_f32_16x16x32_bf16 v[36:39], v[80:83], v[200:203], v[36:39]
	v_mfma_f32_16x16x32_bf16 v[16:19], v[72:75], v[208:211], v[16:19]
	v_mfma_f32_16x16x32_bf16 v[20:23], v[80:83], v[208:211], v[20:23]
	v_mfma_f32_16x16x32_bf16 v[0:3], v[72:75], v[216:219], v[0:3]
	v_mfma_f32_16x16x32_bf16 v[4:7], v[80:83], v[216:219], v[4:7]
	v_mfma_f32_16x16x32_bf16 v[48:51], v[76:79], v[196:199], v[48:51]
	v_mfma_f32_16x16x32_bf16 v[68:71], v[84:87], v[196:199], v[52:55]
	v_mfma_f32_16x16x32_bf16 v[32:35], v[76:79], v[204:207], v[32:35]
	s_add_i32 s93, s93, 2
	v_mfma_f32_16x16x32_bf16 v[36:39], v[84:87], v[204:207], v[36:39]
	s_add_u32 s90, s90, 0x1000
	v_mfma_f32_16x16x32_bf16 v[16:19], v[76:79], v[212:215], v[16:19]
	s_addc_u32 s91, s91, 0
	v_mfma_f32_16x16x32_bf16 v[20:23], v[84:87], v[212:215], v[20:23]
	s_cmp_gt_u32 s93, 61
	v_mfma_f32_16x16x32_bf16 v[0:3], v[76:79], v[220:223], v[0:3]
	s_mov_b64 s[14:15], s[60:61]
	v_mfma_f32_16x16x32_bf16 v[4:7], v[84:87], v[220:223], v[4:7]
	s_barrier
	s_setprio 0
	s_cbranch_scc0 .LBB0_639
	s_and_b64 vcc, exec, s[42:43]
	s_cbranch_vccz .LBB0_642
	s_barrier

.LBB0_771:
	ds_read_b128 v[128:131], v188
	ds_read_b128 v[132:135], v188 offset:1024
	ds_read_b128 v[136:139], v188 offset:2048
	ds_read_b128 v[140:143], v188 offset:3072
	ds_read_b128 v[144:147], v189
	ds_read_b128 v[148:151], v189 offset:1024
	ds_read_b128 v[166:169], v189 offset:2048
	ds_read_b128 v[170:173], v189 offset:3072
	s_add_u32 s3, s38, 0xffd50800
	s_addc_u32 s16, s39, -1
	s_cmpk_eq_i32 s68, 0xa8
	s_cselect_b32 s43, s7, s16
	s_cselect_b32 s42, s6, s3
	s_cselect_b32 s41, s21, s67
	s_cselect_b32 s40, s20, s66
	v_lshl_add_u64 v[192:193], s[38:39], 0, v[158:159]
	s_add_i32 m0, s44, 0xc000
	ds_read_b128 v[174:177], v190
	ds_read_b128 v[178:181], v190 offset:1024
	ds_read_b128 v[182:185], v190 offset:2048
	ds_read_b128 v[196:199], v190 offset:3072
	ds_read_b128 v[200:203], v190 offset:4096
	ds_read_b128 v[204:207], v190 offset:5120
	ds_read_b128 v[208:211], v190 offset:6144
	ds_read_b128 v[212:215], v190 offset:7168
	global_load_lds_dwordx4 v[192:193], off
	v_lshl_add_u64 v[192:193], s[38:39], 0, v[160:161]
	s_add_i32 m0, s44, 0xe000
	s_nop 0
	global_load_lds_dwordx4 v[192:193], off
	s_waitcnt vmcnt(8)
	s_waitcnt lgkmcnt(0)
	s_setprio 1
	s_barrier
	v_mfma_f32_16x16x32_bf16 v[124:127], v[128:131], v[174:177], v[124:127]
	v_mfma_f32_16x16x32_bf16 v[120:123], v[136:139], v[174:177], v[120:123]
	v_mfma_f32_16x16x32_bf16 v[108:111], v[128:131], v[182:185], v[108:111]
	v_mfma_f32_16x16x32_bf16 v[104:107], v[136:139], v[182:185], v[104:107]
	v_mfma_f32_16x16x32_bf16 v[92:95], v[128:131], v[200:203], v[92:95]
	v_mfma_f32_16x16x32_bf16 v[88:91], v[136:139], v[200:203], v[88:91]
	v_mfma_f32_16x16x32_bf16 v[76:79], v[128:131], v[208:211], v[76:79]
	v_mfma_f32_16x16x32_bf16 v[72:75], v[136:139], v[208:211], v[72:75]
	v_mfma_f32_16x16x32_bf16 v[124:127], v[132:135], v[178:181], v[124:127]
	v_mfma_f32_16x16x32_bf16 v[120:123], v[140:143], v[178:181], v[120:123]
	v_mfma_f32_16x16x32_bf16 v[108:111], v[132:135], v[196:199], v[108:111]
	v_mfma_f32_16x16x32_bf16 v[104:107], v[140:143], v[196:199], v[104:107]
	v_mfma_f32_16x16x32_bf16 v[92:95], v[132:135], v[204:207], v[92:95]
	v_mfma_f32_16x16x32_bf16 v[88:91], v[140:143], v[204:207], v[88:91]
	v_mfma_f32_16x16x32_bf16 v[76:79], v[132:135], v[212:215], v[76:79]
	v_mfma_f32_16x16x32_bf16 v[72:75], v[140:143], v[212:215], v[72:75]
	v_mfma_f32_16x16x32_bf16 v[116:119], v[144:147], v[174:177], v[116:119]
	v_mfma_f32_16x16x32_bf16 v[112:115], v[166:169], v[174:177], v[112:115]
	v_mfma_f32_16x16x32_bf16 v[100:103], v[144:147], v[182:185], v[100:103]
	v_mfma_f32_16x16x32_bf16 v[96:99], v[166:169], v[182:185], v[96:99]
	v_mfma_f32_16x16x32_bf16 v[84:87], v[144:147], v[200:203], v[84:87]
	v_mfma_f32_16x16x32_bf16 v[80:83], v[166:169], v[200:203], v[80:83]
	v_mfma_f32_16x16x32_bf16 v[68:71], v[144:147], v[208:211], v[68:71]
	v_mfma_f32_16x16x32_bf16 v[64:67], v[166:169], v[208:211], v[64:67]
	v_mfma_f32_16x16x32_bf16 v[116:119], v[148:151], v[178:181], v[116:119]
	v_mfma_f32_16x16x32_bf16 v[112:115], v[170:173], v[178:181], v[112:115]
	v_mfma_f32_16x16x32_bf16 v[100:103], v[148:151], v[196:199], v[100:103]
	v_mfma_f32_16x16x32_bf16 v[96:99], v[170:173], v[196:199], v[96:99]
	v_mfma_f32_16x16x32_bf16 v[84:87], v[148:151], v[204:207], v[84:87]
	v_mfma_f32_16x16x32_bf16 v[80:83], v[170:173], v[204:207], v[80:83]
	v_mfma_f32_16x16x32_bf16 v[68:71], v[148:151], v[212:215], v[68:71]
	v_mfma_f32_16x16x32_bf16 v[64:67], v[170:173], v[212:215], v[64:67]
	s_barrier
	s_setprio 0
	s_add_i32 s3, s55, s19
	v_lshl_add_u64 v[192:193], s[40:41], 0, v[152:153]
	s_mov_b32 m0, s3
	ds_read_b128 v[174:177], v190 offset:16384
	ds_read_b128 v[178:181], v190 offset:17408
	ds_read_b128 v[182:185], v190 offset:18432
	ds_read_b128 v[196:199], v190 offset:19456
	ds_read_b128 v[200:203], v190 offset:20480
	ds_read_b128 v[204:207], v190 offset:21504
	ds_read_b128 v[208:211], v190 offset:22528
	ds_read_b128 v[212:215], v190 offset:23552
	global_load_lds_dwordx4 v[192:193], off
	s_add_i32 m0, s3, 0x2000
	s_add_u32 s16, s40, 0x2b0000
	v_lshl_add_u64 v[216:217], s[40:41], 0, v[154:155]
	s_addc_u32 s17, s41, 0
	s_add_i32 s3, s56, s19
	global_load_lds_dwordx4 v[216:217], off
	v_lshl_add_u64 v[218:219], s[16:17], 0, v[152:153]
	s_mov_b32 m0, s3
	v_lshl_add_u64 v[220:221], s[42:43], 0, v[154:155]
	global_load_lds_dwordx4 v[218:219], off
	v_lshl_add_u64 v[218:219], s[16:17], 0, v[154:155]
	s_add_i32 m0, s3, 0x2000
	s_nop 0
	global_load_lds_dwordx4 v[218:219], off
	v_lshl_add_u64 v[218:219], s[42:43], 0, v[152:153]
	s_mov_b32 m0, s44
	s_nop 0
	global_load_lds_dwordx4 v[218:219], off
	s_mov_b32 m0, s45
	s_nop 0
	global_load_lds_dwordx4 v[220:221], off
	s_waitcnt vmcnt(8)
	s_waitcnt lgkmcnt(0)
	s_setprio 1
	s_barrier
	v_mfma_f32_16x16x32_bf16 v[60:63], v[128:131], v[174:177], v[60:63]
	v_mfma_f32_16x16x32_bf16 v[56:59], v[136:139], v[174:177], v[56:59]
	v_mfma_f32_16x16x32_bf16 v[44:47], v[128:131], v[182:185], v[44:47]
	v_mfma_f32_16x16x32_bf16 v[40:43], v[136:139], v[182:185], v[40:43]
	v_mfma_f32_16x16x32_bf16 v[28:31], v[128:131], v[200:203], v[28:31]
	v_mfma_f32_16x16x32_bf16 v[24:27], v[136:139], v[200:203], v[24:27]
	v_mfma_f32_16x16x32_bf16 v[12:15], v[128:131], v[208:211], v[12:15]
	v_mfma_f32_16x16x32_bf16 v[8:11], v[136:139], v[208:211], v[8:11]
	v_mfma_f32_16x16x32_bf16 v[60:63], v[132:135], v[178:181], v[60:63]
	v_mfma_f32_16x16x32_bf16 v[56:59], v[140:143], v[178:181], v[56:59]
	v_mfma_f32_16x16x32_bf16 v[44:47], v[132:135], v[196:199], v[44:47]
	v_mfma_f32_16x16x32_bf16 v[40:43], v[140:143], v[196:199], v[40:43]
	v_mfma_f32_16x16x32_bf16 v[28:31], v[132:135], v[204:207], v[28:31]
	v_mfma_f32_16x16x32_bf16 v[24:27], v[140:143], v[204:207], v[24:27]
	v_mfma_f32_16x16x32_bf16 v[12:15], v[132:135], v[212:215], v[12:15]
	v_mfma_f32_16x16x32_bf16 v[8:11], v[140:143], v[212:215], v[8:11]
	v_mfma_f32_16x16x32_bf16 v[52:55], v[144:147], v[174:177], v[52:55]
	v_mfma_f32_16x16x32_bf16 v[48:51], v[166:169], v[174:177], v[48:51]
	v_mfma_f32_16x16x32_bf16 v[36:39], v[144:147], v[182:185], v[36:39]
	v_mfma_f32_16x16x32_bf16 v[32:35], v[166:169], v[182:185], v[32:35]
	v_mfma_f32_16x16x32_bf16 v[20:23], v[144:147], v[200:203], v[20:23]
	v_mfma_f32_16x16x32_bf16 v[16:19], v[166:169], v[200:203], v[16:19]
	v_mfma_f32_16x16x32_bf16 v[4:7], v[144:147], v[208:211], v[4:7]
	v_mfma_f32_16x16x32_bf16 v[0:3], v[166:169], v[208:211], v[0:3]
	v_mfma_f32_16x16x32_bf16 v[52:55], v[148:151], v[178:181], v[52:55]
	v_mfma_f32_16x16x32_bf16 v[48:51], v[170:173], v[178:181], v[48:51]
	v_mfma_f32_16x16x32_bf16 v[36:39], v[148:151], v[196:199], v[36:39]
	v_mfma_f32_16x16x32_bf16 v[32:35], v[170:173], v[196:199], v[32:35]
	v_mfma_f32_16x16x32_bf16 v[20:23], v[148:151], v[204:207], v[20:23]
	v_mfma_f32_16x16x32_bf16 v[16:19], v[170:173], v[204:207], v[16:19]
	v_mfma_f32_16x16x32_bf16 v[4:7], v[148:151], v[212:215], v[4:7]
	v_mfma_f32_16x16x32_bf16 v[0:3], v[170:173], v[212:215], v[0:3]
	s_barrier
	s_setprio 0
	s_add_i32 s3, 0, 0x18000
	s_add_i32 s33, 0, 0x1c000
	v_add_u32_e32 v140, s3, v187
	v_add_u32_e32 v170, s33, v187
	ds_read_b128 v[128:131], v140
	ds_read_b128 v[132:135], v140 offset:1024
	ds_read_b128 v[136:139], v140 offset:2048
	ds_read_b128 v[140:143], v140 offset:3072
	ds_read_b128 v[144:147], v170
	ds_read_b128 v[148:151], v170 offset:1024
	ds_read_b128 v[166:169], v170 offset:2048
	ds_read_b128 v[170:173], v170 offset:3072
	s_add_u32 s16, s42, 0x2b0000
	s_addc_u32 s17, s43, 0
	s_mov_b32 m0, s46
	v_lshl_add_u64 v[222:223], s[16:17], 0, v[152:153]
	ds_read_b128 v[174:177], v190 offset:32768
	ds_read_b128 v[178:181], v190 offset:33792
	ds_read_b128 v[182:185], v190 offset:34816
	ds_read_b128 v[196:199], v190 offset:35840
	ds_read_b128 v[200:203], v190 offset:36864
	ds_read_b128 v[204:207], v190 offset:37888
	ds_read_b128 v[208:211], v190 offset:38912
	ds_read_b128 v[212:215], v190 offset:39936
	global_load_lds_dwordx4 v[222:223], off
	v_lshl_add_u64 v[222:223], s[16:17], 0, v[154:155]
	s_mov_b32 m0, s47
	s_nop 0
	global_load_lds_dwordx4 v[222:223], off
	s_waitcnt vmcnt(8)
	s_waitcnt lgkmcnt(0)
	s_setprio 1
	s_barrier
	v_mfma_f32_16x16x32_bf16 v[124:127], v[128:131], v[174:177], v[124:127]
	v_mfma_f32_16x16x32_bf16 v[120:123], v[136:139], v[174:177], v[120:123]
	v_mfma_f32_16x16x32_bf16 v[108:111], v[128:131], v[182:185], v[108:111]
	v_mfma_f32_16x16x32_bf16 v[104:107], v[136:139], v[182:185], v[104:107]
	v_mfma_f32_16x16x32_bf16 v[92:95], v[128:131], v[200:203], v[92:95]
	v_mfma_f32_16x16x32_bf16 v[88:91], v[136:139], v[200:203], v[88:91]
	v_mfma_f32_16x16x32_bf16 v[76:79], v[128:131], v[208:211], v[76:79]
	v_mfma_f32_16x16x32_bf16 v[72:75], v[136:139], v[208:211], v[72:75]
	v_mfma_f32_16x16x32_bf16 v[124:127], v[132:135], v[178:181], v[124:127]
	v_mfma_f32_16x16x32_bf16 v[120:123], v[140:143], v[178:181], v[120:123]
	v_mfma_f32_16x16x32_bf16 v[108:111], v[132:135], v[196:199], v[108:111]
	v_mfma_f32_16x16x32_bf16 v[104:107], v[140:143], v[196:199], v[104:107]
	v_mfma_f32_16x16x32_bf16 v[92:95], v[132:135], v[204:207], v[92:95]
	v_mfma_f32_16x16x32_bf16 v[88:91], v[140:143], v[204:207], v[88:91]
	v_mfma_f32_16x16x32_bf16 v[76:79], v[132:135], v[212:215], v[76:79]
	v_mfma_f32_16x16x32_bf16 v[72:75], v[140:143], v[212:215], v[72:75]
	v_mfma_f32_16x16x32_bf16 v[116:119], v[144:147], v[174:177], v[116:119]
	v_mfma_f32_16x16x32_bf16 v[112:115], v[166:169], v[174:177], v[112:115]
	v_mfma_f32_16x16x32_bf16 v[100:103], v[144:147], v[182:185], v[100:103]
	v_mfma_f32_16x16x32_bf16 v[96:99], v[166:169], v[182:185], v[96:99]
	v_mfma_f32_16x16x32_bf16 v[84:87], v[144:147], v[200:203], v[84:87]
	v_mfma_f32_16x16x32_bf16 v[80:83], v[166:169], v[200:203], v[80:83]
	v_mfma_f32_16x16x32_bf16 v[68:71], v[144:147], v[208:211], v[68:71]
	v_mfma_f32_16x16x32_bf16 v[64:67], v[166:169], v[208:211], v[64:67]
	v_mfma_f32_16x16x32_bf16 v[116:119], v[148:151], v[178:181], v[116:119]
	v_mfma_f32_16x16x32_bf16 v[112:115], v[170:173], v[178:181], v[112:115]
	v_mfma_f32_16x16x32_bf16 v[100:103], v[148:151], v[196:199], v[100:103]
	v_mfma_f32_16x16x32_bf16 v[96:99], v[170:173], v[196:199], v[96:99]
	v_mfma_f32_16x16x32_bf16 v[84:87], v[148:151], v[204:207], v[84:87]
	v_mfma_f32_16x16x32_bf16 v[80:83], v[170:173], v[204:207], v[80:83]
	v_mfma_f32_16x16x32_bf16 v[68:71], v[148:151], v[212:215], v[68:71]
	v_mfma_f32_16x16x32_bf16 v[64:67], v[170:173], v[212:215], v[64:67]
	s_barrier
	s_setprio 0
	s_add_i32 s3, s3, s19
	v_lshl_add_u64 v[192:193], v[192:193], 0, s[12:13]
	s_mov_b32 m0, s3
	ds_read_b128 v[174:177], v190 offset:49152
	ds_read_b128 v[178:181], v190 offset:50176
	ds_read_b128 v[182:185], v190 offset:51200
	ds_read_b128 v[196:199], v190 offset:52224
	ds_read_b128 v[200:203], v190 offset:53248
	ds_read_b128 v[204:207], v190 offset:54272
	ds_read_b128 v[208:211], v190 offset:55296
	ds_read_b128 v[212:215], v190 offset:56320
	global_load_lds_dwordx4 v[192:193], off
	s_add_i32 m0, s3, 0x2000
	s_add_u32 s16, s40, 0x2b0800
	v_lshl_add_u64 v[192:193], v[216:217], 0, s[12:13]
	s_addc_u32 s17, s41, 0
	s_add_i32 s3, s33, s19
	global_load_lds_dwordx4 v[192:193], off
	v_lshl_add_u64 v[192:193], s[16:17], 0, v[152:153]
	s_mov_b32 m0, s3
	s_nop 0
	global_load_lds_dwordx4 v[192:193], off
	v_lshl_add_u64 v[192:193], s[16:17], 0, v[154:155]
	s_add_i32 m0, s3, 0x2000
	s_nop 0
	global_load_lds_dwordx4 v[192:193], off
	v_lshl_add_u64 v[192:193], v[218:219], 0, s[12:13]
	s_mov_b32 m0, s50
	s_nop 0
	global_load_lds_dwordx4 v[192:193], off
	v_lshl_add_u64 v[192:193], v[220:221], 0, s[12:13]
	s_mov_b32 m0, s51
	s_nop 0
	global_load_lds_dwordx4 v[192:193], off
	s_waitcnt vmcnt(8)
	s_waitcnt lgkmcnt(0)
	s_setprio 1
	s_barrier
	v_mfma_f32_16x16x32_bf16 v[60:63], v[128:131], v[174:177], v[60:63]
	v_mfma_f32_16x16x32_bf16 v[56:59], v[136:139], v[174:177], v[56:59]
	v_mfma_f32_16x16x32_bf16 v[44:47], v[128:131], v[182:185], v[44:47]
	v_mfma_f32_16x16x32_bf16 v[40:43], v[136:139], v[182:185], v[40:43]
	v_mfma_f32_16x16x32_bf16 v[28:31], v[128:131], v[200:203], v[28:31]
	v_mfma_f32_16x16x32_bf16 v[24:27], v[136:139], v[200:203], v[24:27]
	v_mfma_f32_16x16x32_bf16 v[12:15], v[128:131], v[208:211], v[12:15]
	v_mfma_f32_16x16x32_bf16 v[8:11], v[136:139], v[208:211], v[8:11]
	v_mfma_f32_16x16x32_bf16 v[60:63], v[132:135], v[178:181], v[60:63]
	v_mfma_f32_16x16x32_bf16 v[56:59], v[140:143], v[178:181], v[56:59]
	v_mfma_f32_16x16x32_bf16 v[44:47], v[132:135], v[196:199], v[44:47]
	v_mfma_f32_16x16x32_bf16 v[40:43], v[140:143], v[196:199], v[40:43]
	v_mfma_f32_16x16x32_bf16 v[28:31], v[132:135], v[204:207], v[28:31]
	v_mfma_f32_16x16x32_bf16 v[24:27], v[140:143], v[204:207], v[24:27]
	v_mfma_f32_16x16x32_bf16 v[12:15], v[132:135], v[212:215], v[12:15]
	v_mfma_f32_16x16x32_bf16 v[8:11], v[140:143], v[212:215], v[8:11]
	v_mfma_f32_16x16x32_bf16 v[52:55], v[144:147], v[174:177], v[52:55]
	v_mfma_f32_16x16x32_bf16 v[48:51], v[166:169], v[174:177], v[48:51]
	v_mfma_f32_16x16x32_bf16 v[36:39], v[144:147], v[182:185], v[36:39]
	v_mfma_f32_16x16x32_bf16 v[32:35], v[166:169], v[182:185], v[32:35]
	v_mfma_f32_16x16x32_bf16 v[20:23], v[144:147], v[200:203], v[20:23]
	v_mfma_f32_16x16x32_bf16 v[16:19], v[166:169], v[200:203], v[16:19]
	v_mfma_f32_16x16x32_bf16 v[4:7], v[144:147], v[208:211], v[4:7]
	v_mfma_f32_16x16x32_bf16 v[0:3], v[166:169], v[208:211], v[0:3]
	v_mfma_f32_16x16x32_bf16 v[52:55], v[148:151], v[178:181], v[52:55]
	v_mfma_f32_16x16x32_bf16 v[48:51], v[170:173], v[178:181], v[48:51]
	v_mfma_f32_16x16x32_bf16 v[36:39], v[148:151], v[196:199], v[36:39]
	s_add_i32 s68, s68, 2
	v_mfma_f32_16x16x32_bf16 v[32:35], v[170:173], v[196:199], v[32:35]
	s_add_u32 s38, s38, 0x1000
	v_mfma_f32_16x16x32_bf16 v[20:23], v[148:151], v[204:207], v[20:23]
	s_addc_u32 s39, s39, 0
	v_mfma_f32_16x16x32_bf16 v[16:19], v[170:173], v[204:207], v[16:19]
	s_add_u32 s66, s66, 0x1000
	v_mfma_f32_16x16x32_bf16 v[4:7], v[148:151], v[212:215], v[4:7]
	s_addc_u32 s67, s67, 0
	v_mfma_f32_16x16x32_bf16 v[0:3], v[170:173], v[212:215], v[0:3]
	s_cmpk_gt_u32 s68, 0xa9
	s_barrier
	s_setprio 0
	s_cbranch_scc0 .LBB0_771
	s_and_b64 vcc, exec, s[14:15]
	s_cbranch_vccz .LBB0_774
	s_barrier
